# G10 epilogue: 8 gate loads hoisted (no per-row vmcnt(0) drain); G3+G4: mid first-half 16 gate loads issued together, final epilogue second-half gate loads hoisted before first-half stores
# baseline (speedup 1.0000x reference)
; __device__ __forceinline__ unsigned xb_ld(unsigned* p)              { return __hip_atomic_load(p, __ATOMIC_RELAXED, __HIP_MEMORY_SCOPE_AGENT); }
; __device__ __forceinline__ unsigned xb_add(unsigned* p, unsigned v) { return __hip_atomic_fetch_add(p, v, __ATOMIC_RELAXED, __HIP_MEMORY_SCOPE_AGENT); }
; #define XB_SPIN(cond, bar) do { unsigned _sp = 0; while (cond) { __builtin_amdgcn_s_sleep(1); \
;     if ((++_sp & 255u) == 0u) { if (xb_ld(&(bar)[XB_TMO])) break; if (_sp > XB_SPIN_CAP) { atomicAdd(&(bar)[XB_TMO], 1u); break; } } } } while (0)
; __device__ __forceinline__ void xcd_barrier(unsigned* bar, volatile LAS unsigned* st) {
;     ...
;         const unsigned old = xb_add(&bar[XB_XSUB(x)], 1u);
;         const unsigned gen = old / nloc;
;         if (old + 1u == (gen + 1u) * nloc) {
;             __builtin_amdgcn_fence(__ATOMIC_RELEASE, "agent");
;             asm volatile("s_waitcnt vmcnt(0)" ::: "memory");
;             const unsigned og = xb_add(&bar[XB_TOP], 1u);
;             const unsigned tg = og / nx;
;             if (og + 1u == (tg + 1u) * nx) xb_add(&bar[XB_TOPGEN], 1u);
;             else XB_SPIN(xb_ld(&bar[XB_TOPGEN]) == tg, bar);
;             __builtin_amdgcn_fence(__ATOMIC_ACQUIRE, "agent");
;             xb_add(&bar[XB_XGEN(x)], 1u);
;             asm volatile("s_waitcnt vmcnt(0)" ::: "memory");
;         } else {
;             XB_SPIN(xb_ld(&bar[XB_XGEN(x)]) == gen, bar);
.LBB0_111:
	s_or_b64 exec, exec, s[10:11]
	v_cvt_f32_u32_e32 v3, v0
	s_waitcnt vmcnt(0)
	v_readfirstlane_b32 s8, v2
	s_add_u32 s10, s4, 0x39403500
	s_addc_u32 s11, s5, 0
	v_rcp_iflag_f32_e32 v3, v3
	v_add_u32_e32 v1, s8, v1
	v_add_u32_e32 v4, 1, v1
	s_mov_b64 s[12:13], -1
	v_mul_f32_e32 v2, 0x4f7ffffe, v3
	v_cvt_u32_f32_e32 v2, v2
	v_sub_u32_e32 v3, 0, v0
	v_mul_lo_u32 v3, v3, v2
	v_mul_hi_u32 v3, v2, v3
	v_add_u32_e32 v2, v2, v3
	v_mul_hi_u32 v2, v1, v2
	v_mul_lo_u32 v3, v2, v0
	v_sub_u32_e32 v1, v1, v3
	v_add_u32_e32 v5, 1, v2
	v_cmp_ge_u32_e32 vcc, v1, v0
	v_sub_u32_e32 v3, v1, v0
	s_nop 0
	v_cndmask_b32_e32 v2, v2, v5, vcc
	v_cndmask_b32_e32 v1, v1, v3, vcc
	v_add_u32_e32 v3, 1, v2
	v_cmp_ge_u32_e32 vcc, v1, v0
	s_nop 1
	v_cndmask_b32_e32 v2, v2, v3, vcc
	v_mul_lo_u32 v1, v0, v2
	v_add_u32_e32 v0, v1, v0
	v_cmp_ne_u32_e32 vcc, v4, v0
	v_mov_b64_e32 v[0:1], s[10:11]
	s_and_saveexec_b64 s[8:9], vcc
	s_cbranch_execz .LBB0_123
	v_mov_b32_e32 v0, 0
	global_load_dword v1, v0, s[10:11] sc1
	s_mov_b64 s[16:17], 0
	s_waitcnt vmcnt(0)
	v_cmp_eq_u32_e32 vcc, v1, v2
	s_and_saveexec_b64 s[14:15], vcc
	s_cbranch_execz .LBB0_122
	s_add_u32 s12, s4, 0x39400200
	s_addc_u32 s13, s5, 0
	s_mov_b32 s24, 1
	s_mov_b64 s[4:5], 0
	s_branch .LBB0_115

; __device__ __forceinline__ unsigned xb_ld(unsigned* p)              { return __hip_atomic_load(p, __ATOMIC_RELAXED, __HIP_MEMORY_SCOPE_AGENT); }
; __device__ __forceinline__ unsigned xb_add(unsigned* p, unsigned v) { return __hip_atomic_fetch_add(p, v, __ATOMIC_RELAXED, __HIP_MEMORY_SCOPE_AGENT); }
; #define XB_SPIN(cond, bar) do { unsigned _sp = 0; while (cond) { __builtin_amdgcn_s_sleep(1); \
;     if ((++_sp & 255u) == 0u) { if (xb_ld(&(bar)[XB_TMO])) break; if (_sp > XB_SPIN_CAP) { atomicAdd(&(bar)[XB_TMO], 1u); break; } } } } while (0)
; __device__ __forceinline__ void xcd_barrier(unsigned* bar, volatile LAS unsigned* st) {
;     ...
;             const unsigned og = xb_add(&bar[XB_TOP], 1u);
;             const unsigned tg = og / nx;
;             if (og + 1u == (tg + 1u) * nx) xb_add(&bar[XB_TOPGEN], 1u);
;             else XB_SPIN(xb_ld(&bar[XB_TOPGEN]) == tg, bar);
;             __builtin_amdgcn_fence(__ATOMIC_ACQUIRE, "agent");
;             xb_add(&bar[XB_XGEN(x)], 1u);
;             asm volatile("s_waitcnt vmcnt(0)" ::: "memory");
.LBB0_123:
	s_or_b64 exec, exec, s[8:9]
	s_and_saveexec_b64 s[4:5], s[12:13]
	s_cbranch_execz .LBB0_125
	v_mov_b32_e32 v2, 1
	global_atomic_add v[0:1], v2, off
.LBB0_125:
	s_or_b64 exec, exec, s[4:5]
	s_mov_b64 s[4:5], exec
	v_mbcnt_lo_u32_b32 v0, s4, 0
	v_mbcnt_hi_u32_b32 v0, s5, v0
	v_cmp_eq_u32_e32 vcc, 0, v0
	s_waitcnt vmcnt(0)
	buffer_inv sc1
	s_and_saveexec_b64 s[8:9], vcc
	s_cbranch_execz .LBB0_127
	s_bcnt1_i32_b64 s4, s[4:5]
	v_mov_b32_e32 v0, 0x2000
	v_mov_b32_e32 v1, s4
	global_atomic_add v0, v1, s[6:7] offset:1024

; __device__ __forceinline__ unsigned xb_ld(unsigned* p)              { return __hip_atomic_load(p, __ATOMIC_RELAXED, __HIP_MEMORY_SCOPE_AGENT); }
; __device__ __forceinline__ unsigned xb_add(unsigned* p, unsigned v) { return __hip_atomic_fetch_add(p, v, __ATOMIC_RELAXED, __HIP_MEMORY_SCOPE_AGENT); }
; #define XB_SPIN(cond, bar) do { unsigned _sp = 0; while (cond) { __builtin_amdgcn_s_sleep(1); \
;     if ((++_sp & 255u) == 0u) { if (xb_ld(&(bar)[XB_TMO])) break; if (_sp > XB_SPIN_CAP) { atomicAdd(&(bar)[XB_TMO], 1u); break; } } } } while (0)
; __device__ __forceinline__ void xcd_barrier(unsigned* bar, volatile LAS unsigned* st) {
;     ...
;         const unsigned old = xb_add(&bar[XB_XSUB(x)], 1u);
;         const unsigned gen = old / nloc;
;         if (old + 1u == (gen + 1u) * nloc) {
;             __builtin_amdgcn_fence(__ATOMIC_RELEASE, "agent");
;             asm volatile("s_waitcnt vmcnt(0)" ::: "memory");
;             const unsigned og = xb_add(&bar[XB_TOP], 1u);
;             const unsigned tg = og / nx;
;             if (og + 1u == (tg + 1u) * nx) xb_add(&bar[XB_TOPGEN], 1u);
;             else XB_SPIN(xb_ld(&bar[XB_TOPGEN]) == tg, bar);
;             __builtin_amdgcn_fence(__ATOMIC_ACQUIRE, "agent");
;             xb_add(&bar[XB_XGEN(x)], 1u);
;             asm volatile("s_waitcnt vmcnt(0)" ::: "memory");
;         } else {
;             XB_SPIN(xb_ld(&bar[XB_XGEN(x)]) == gen, bar);
.LBB0_296:
	s_or_b64 exec, exec, s[10:11]
	s_waitcnt vmcnt(0)
	v_readfirstlane_b32 s8, v2
	v_cvt_f32_u32_e32 v2, v0
	v_sub_u32_e32 v3, 0, v0
	v_add_u32_e32 v1, s8, v1
	s_add_u32 s8, s4, 0x39403500
	v_rcp_iflag_f32_e32 v2, v2
	s_addc_u32 s9, s5, 0
	s_mov_b64 s[12:13], -1
	v_mul_f32_e32 v2, 0x4f7ffffe, v2
	v_cvt_u32_f32_e32 v2, v2
	v_mul_lo_u32 v3, v3, v2
	v_mul_hi_u32 v3, v2, v3
	v_add_u32_e32 v2, v2, v3
	v_mul_hi_u32 v2, v1, v2
	v_mul_lo_u32 v3, v2, v0
	v_sub_u32_e32 v3, v1, v3
	v_cmp_ge_u32_e32 vcc, v3, v0
	v_add_u32_e32 v4, 1, v2
	v_add_u32_e32 v1, 1, v1
	v_cndmask_b32_e32 v2, v2, v4, vcc
	v_sub_u32_e32 v4, v3, v0
	v_cndmask_b32_e32 v3, v3, v4, vcc
	v_cmp_ge_u32_e32 vcc, v3, v0
	v_add_u32_e32 v3, 1, v2
	s_nop 0
	v_cndmask_b32_e32 v2, v2, v3, vcc
	v_mul_lo_u32 v3, v0, v2
	v_add_u32_e32 v0, v3, v0
	v_cmp_ne_u32_e32 vcc, v1, v0
	v_mov_b64_e32 v[0:1], s[8:9]
	s_and_saveexec_b64 s[10:11], vcc
	s_cbranch_execz .LBB0_308
	global_load_dword v0, v195, s[8:9] sc1
	s_mov_b64 s[16:17], 0
	s_waitcnt vmcnt(0)
	v_cmp_eq_u32_e32 vcc, v0, v2
	s_and_saveexec_b64 s[14:15], vcc
	s_cbranch_execz .LBB0_307
	s_add_u32 s12, s4, 0x39400200
	s_addc_u32 s13, s5, 0
	s_mov_b32 s24, 1
	s_mov_b64 s[4:5], 0
	s_branch .LBB0_300

; __device__ __forceinline__ unsigned xb_ld(unsigned* p)              { return __hip_atomic_load(p, __ATOMIC_RELAXED, __HIP_MEMORY_SCOPE_AGENT); }
; __device__ __forceinline__ unsigned xb_add(unsigned* p, unsigned v) { return __hip_atomic_fetch_add(p, v, __ATOMIC_RELAXED, __HIP_MEMORY_SCOPE_AGENT); }
; #define XB_SPIN(cond, bar) do { unsigned _sp = 0; while (cond) { __builtin_amdgcn_s_sleep(1); \
;     if ((++_sp & 255u) == 0u) { if (xb_ld(&(bar)[XB_TMO])) break; if (_sp > XB_SPIN_CAP) { atomicAdd(&(bar)[XB_TMO], 1u); break; } } } } while (0)
; __device__ __forceinline__ void xcd_barrier(unsigned* bar, volatile LAS unsigned* st) {
;     ...
;             const unsigned og = xb_add(&bar[XB_TOP], 1u);
;             const unsigned tg = og / nx;
;             if (og + 1u == (tg + 1u) * nx) xb_add(&bar[XB_TOPGEN], 1u);
;             else XB_SPIN(xb_ld(&bar[XB_TOPGEN]) == tg, bar);
;             __builtin_amdgcn_fence(__ATOMIC_ACQUIRE, "agent");
;             xb_add(&bar[XB_XGEN(x)], 1u);
;             asm volatile("s_waitcnt vmcnt(0)" ::: "memory");
.LBB0_308:
	s_or_b64 exec, exec, s[10:11]
	s_and_saveexec_b64 s[4:5], s[12:13]
	s_cbranch_execz .LBB0_310
	global_atomic_add v[0:1], v226, off
.LBB0_310:
	s_or_b64 exec, exec, s[4:5]
	s_mov_b64 s[4:5], exec
	v_mbcnt_lo_u32_b32 v0, s4, 0
	v_mbcnt_hi_u32_b32 v0, s5, v0
	v_cmp_eq_u32_e32 vcc, 0, v0
	s_waitcnt vmcnt(0)
	buffer_inv sc1
	s_and_saveexec_b64 s[8:9], vcc
	s_cbranch_execz .LBB0_312
	s_bcnt1_i32_b64 s4, s[4:5]
	v_mov_b32_e32 v0, s4
	global_atomic_add v223, v0, s[6:7] offset:1024

; __device__ __forceinline__ float bf_lo(unsigned u) { return __uint_as_float(u << 16); }
; __device__ __forceinline__ float bf_hi(unsigned u) { return __uint_as_float(u & 0xffff0000u); }
;     __device__ __forceinline__ void mid(f32x4 (&acc)[2][2][4][2], const Unit& u, int wr, int wc, int fr, int fq) const {
;     ...
;             for (int m = 0; m < 4; ++m)
; #pragma unroll
;                 for (int bj = 0; bj < 2; ++bj) { sa[m][bj] = *(const u32x4*)(sg + off + m * 16 * 2048 + bj * HALF); sb[m][bj] = *(const u32x4*)(sg + off + m * 16 * 2048 + 1024 + bj * HALF); }
; #pragma unroll
;             for (int m = 0; m < 4; ++m)
; #pragma unroll
;                 for (int bj = 0; bj < 2; ++bj) {
;                     const unsigned av[4] = {sa[m][bj].x, sa[m][bj].y, sa[m][bj].z, sa[m][bj].w}, bv[4] = {sb[m][bj].x, sb[m][bj].y, sb[m][bj].z, sb[m][bj].w};
; #pragma unroll
;                     for (int q = 0; q < 4; ++q) { const float r0 = bf_lo(av[q]) * __builtin_amdgcn_rcpf(fmaxf(bf_lo(bv[q]), 1e-30f)), r1 = bf_hi(av[q]) * __builtin_amdgcn_rcpf(fmaxf(bf_hi(bv[q]), 1e-30f));
;                         acc[ai][bj][m][q >> 1][(q & 1) * 2] *= r0; acc[ai][bj][m][q >> 1][(q & 1) * 2 + 1] *= r1; } }
.LBB0_423:
	s_cmpk_lg_i32 s26, 0x400
	s_cbranch_scc1 .LBB0_422
	v_mov_b32_e32 v194, v218
	s_nop 0
	v_lshl_add_u64 v[128:129], v[194:195], 1, s[10:11]
	global_load_dwordx4 v[184:187], v[128:129], off
	global_load_dwordx4 v[188:191], v[128:129], off offset:2048
	global_load_dwordx4 v[176:179], v[128:129], off offset:256
	global_load_dwordx4 v[180:183], v[128:129], off offset:2304
	v_add_co_u32_e32 v130, vcc, s72, v128
	v_add_u32_e32 v194, 0x40000, v194
	s_nop 0
	v_addc_co_u32_e32 v131, vcc, 0, v129, vcc
	global_load_dwordx4 v[168:171], v[130:131], off
	global_load_dwordx4 v[172:175], v[130:131], off offset:2048
	global_load_dwordx4 v[160:163], v[130:131], off offset:256
	global_load_dwordx4 v[164:167], v[130:131], off offset:2304
	v_add_co_u32_e32 v134, vcc, s43, v128
	s_nop 1
	v_addc_co_u32_e32 v135, vcc, 0, v129, vcc
	global_load_dwordx4 v[152:155], v[134:135], off
	global_load_dwordx4 v[156:159], v[134:135], off offset:2048
	global_load_dwordx4 v[144:147], v[134:135], off offset:256
	global_load_dwordx4 v[148:151], v[134:135], off offset:2304
	v_add_co_u32_e32 v132, vcc, s60, v128
	s_nop 1
	v_addc_co_u32_e32 v133, vcc, 0, v129, vcc
	global_load_dwordx4 v[136:139], v[132:133], off
	global_load_dwordx4 v[140:143], v[132:133], off offset:2048
	global_load_dwordx4 v[128:131], v[132:133], off offset:256
	s_nop 0
	global_load_dwordx4 v[132:135], v[132:133], off offset:2304
	s_waitcnt vmcnt(0)
	v_lshlrev_b32_e32 v240, 16, v184
	v_lshlrev_b32_e32 v219, 16, v188
	v_and_b32_e32 v188, 0xffff0000, v188
	v_and_b32_e32 v241, 0xffff0000, v184
	v_lshlrev_b32_e32 v184, 16, v189
	v_max_f32_e32 v188, v188, v188
	v_max_f32_e32 v184, v184, v184
	v_max_f32_e32 v188, 0xda24260, v188
	v_max_f32_e32 v184, 0xda24260, v184
	v_rcp_f32_e32 v239, v188
	v_rcp_f32_e32 v188, v184
	v_and_b32_e32 v184, 0xffff0000, v189
	v_max_f32_e32 v184, v184, v184
	v_max_f32_e32 v184, 0xda24260, v184
	v_rcp_f32_e32 v189, v184
	v_lshlrev_b32_e32 v184, 16, v185
	v_and_b32_e32 v185, 0xffff0000, v185
	v_pk_mul_f32 v[184:185], v[188:189], v[184:185]
	v_lshlrev_b32_e32 v188, 16, v186
	v_pk_mul_f32 v[126:127], v[126:127], v[184:185]
	v_lshlrev_b32_e32 v184, 16, v190
	v_and_b32_e32 v185, 0xffff0000, v190
	v_max_f32_e32 v184, v184, v184
	v_max_f32_e32 v185, v185, v185
	v_max_f32_e32 v184, 0xda24260, v184
	v_max_f32_e32 v185, 0xda24260, v185
	v_rcp_f32_e32 v184, v184
	v_rcp_f32_e32 v185, v185
	v_and_b32_e32 v189, 0xffff0000, v186
	v_lshlrev_b32_e32 v186, 16, v187
	v_and_b32_e32 v187, 0xffff0000, v187
	v_pk_mul_f32 v[184:185], v[184:185], v[188:189]
	v_pk_mul_f32 v[120:121], v[120:121], v[184:185]
	v_lshlrev_b32_e32 v184, 16, v191
	v_and_b32_e32 v185, 0xffff0000, v191
	v_max_f32_e32 v184, v184, v184
	v_max_f32_e32 v185, v185, v185
	v_max_f32_e32 v184, 0xda24260, v184
	v_max_f32_e32 v185, 0xda24260, v185
	v_rcp_f32_e32 v184, v184
	v_rcp_f32_e32 v185, v185
	v_max_f32_e32 v219, v219, v219
	v_pk_mul_f32 v[184:185], v[184:185], v[186:187]
	v_lshlrev_b32_e32 v186, 16, v176
	v_pk_mul_f32 v[122:123], v[122:123], v[184:185]
	v_lshlrev_b32_e32 v184, 16, v180
	v_and_b32_e32 v180, 0xffff0000, v180
	v_and_b32_e32 v187, 0xffff0000, v176
	v_lshlrev_b32_e32 v176, 16, v181
	v_max_f32_e32 v180, v180, v180
	v_max_f32_e32 v176, v176, v176
	v_max_f32_e32 v180, 0xda24260, v180
	v_max_f32_e32 v176, 0xda24260, v176
	v_rcp_f32_e32 v185, v180
	v_rcp_f32_e32 v180, v176
	v_and_b32_e32 v176, 0xffff0000, v181
	v_max_f32_e32 v176, v176, v176
	v_max_f32_e32 v176, 0xda24260, v176
	v_rcp_f32_e32 v181, v176
	v_lshlrev_b32_e32 v176, 16, v177
	v_and_b32_e32 v177, 0xffff0000, v177
	v_pk_mul_f32 v[176:177], v[180:181], v[176:177]
	v_lshlrev_b32_e32 v180, 16, v178
	v_pk_mul_f32 v[118:119], v[118:119], v[176:177]
	v_lshlrev_b32_e32 v176, 16, v182
	v_and_b32_e32 v177, 0xffff0000, v182
	v_max_f32_e32 v176, v176, v176
	v_max_f32_e32 v177, v177, v177
	v_max_f32_e32 v176, 0xda24260, v176
	v_max_f32_e32 v177, 0xda24260, v177
	v_rcp_f32_e32 v176, v176
	v_rcp_f32_e32 v177, v177
	v_and_b32_e32 v181, 0xffff0000, v178
	v_lshlrev_b32_e32 v178, 16, v179
	v_and_b32_e32 v179, 0xffff0000, v179
	v_pk_mul_f32 v[176:177], v[176:177], v[180:181]
	v_pk_mul_f32 v[112:113], v[112:113], v[176:177]
	v_lshlrev_b32_e32 v176, 16, v183
	v_and_b32_e32 v177, 0xffff0000, v183
	v_max_f32_e32 v176, v176, v176
	v_max_f32_e32 v177, v177, v177
	v_max_f32_e32 v176, 0xda24260, v176
	v_max_f32_e32 v177, 0xda24260, v177
	v_rcp_f32_e32 v176, v176
	v_rcp_f32_e32 v177, v177
	v_max_f32_e32 v184, v184, v184
	v_max_f32_e32 v184, 0xda24260, v184
	v_pk_mul_f32 v[176:177], v[176:177], v[178:179]
	v_lshlrev_b32_e32 v178, 16, v168
	v_pk_mul_f32 v[114:115], v[114:115], v[176:177]
	v_lshlrev_b32_e32 v176, 16, v172
	v_and_b32_e32 v172, 0xffff0000, v172
	v_and_b32_e32 v179, 0xffff0000, v168
	v_lshlrev_b32_e32 v168, 16, v173
	v_max_f32_e32 v172, v172, v172
	v_max_f32_e32 v168, v168, v168
	v_max_f32_e32 v172, 0xda24260, v172
	v_max_f32_e32 v168, 0xda24260, v168
	v_rcp_f32_e32 v177, v172
	v_rcp_f32_e32 v172, v168
	v_and_b32_e32 v168, 0xffff0000, v173
	v_max_f32_e32 v168, v168, v168
	v_max_f32_e32 v168, 0xda24260, v168
	v_rcp_f32_e32 v173, v168
	v_lshlrev_b32_e32 v168, 16, v169
	v_and_b32_e32 v169, 0xffff0000, v169
	v_max_f32_e32 v176, v176, v176
	v_pk_mul_f32 v[168:169], v[172:173], v[168:169]
	v_lshlrev_b32_e32 v172, 16, v170
	v_pk_mul_f32 v[110:111], v[110:111], v[168:169]
	v_lshlrev_b32_e32 v168, 16, v174
	v_and_b32_e32 v169, 0xffff0000, v174
	v_max_f32_e32 v168, v168, v168
	v_max_f32_e32 v169, v169, v169
	v_max_f32_e32 v168, 0xda24260, v168
	v_max_f32_e32 v169, 0xda24260, v169
	v_rcp_f32_e32 v168, v168
	v_rcp_f32_e32 v169, v169
	v_and_b32_e32 v173, 0xffff0000, v170
	v_lshlrev_b32_e32 v170, 16, v171
; __device__ __forceinline__ float bf_lo(unsigned u) { return __uint_as_float(u << 16); }
; __device__ __forceinline__ float bf_hi(unsigned u) { return __uint_as_float(u & 0xffff0000u); }
;     __device__ __forceinline__ void mid(f32x4 (&acc)[2][2][4][2], const Unit& u, int wr, int wc, int fr, int fq) const {
;     ...
;             for (int m = 0; m < 4; ++m)
; #pragma unroll
;                 for (int bj = 0; bj < 2; ++bj) {
;                     const unsigned av[4] = {sa[m][bj].x, sa[m][bj].y, sa[m][bj].z, sa[m][bj].w}, bv[4] = {sb[m][bj].x, sb[m][bj].y, sb[m][bj].z, sb[m][bj].w};
; #pragma unroll
;                     for (int q = 0; q < 4; ++q) { const float r0 = bf_lo(av[q]) * __builtin_amdgcn_rcpf(fmaxf(bf_lo(bv[q]), 1e-30f)), r1 = bf_hi(av[q]) * __builtin_amdgcn_rcpf(fmaxf(bf_hi(bv[q]), 1e-30f));
;                         acc[ai][bj][m][q >> 1][(q & 1) * 2] *= r0; acc[ai][bj][m][q >> 1][(q & 1) * 2 + 1] *= r1; } }
;             off += 128u * 2048u; }
	v_and_b32_e32 v171, 0xffff0000, v171
	v_pk_mul_f32 v[168:169], v[168:169], v[172:173]
	v_max_f32_e32 v176, 0xda24260, v176
	v_pk_mul_f32 v[104:105], v[104:105], v[168:169]
	v_lshlrev_b32_e32 v168, 16, v175
	v_and_b32_e32 v169, 0xffff0000, v175
	v_max_f32_e32 v168, v168, v168
	v_max_f32_e32 v169, v169, v169
	v_max_f32_e32 v168, 0xda24260, v168
	v_max_f32_e32 v169, 0xda24260, v169
	v_rcp_f32_e32 v168, v168
	v_rcp_f32_e32 v169, v169
	v_rcp_f32_e32 v176, v176
	v_rcp_f32_e32 v184, v184
	v_max_f32_e32 v219, 0xda24260, v219
	v_pk_mul_f32 v[168:169], v[168:169], v[170:171]
	v_lshlrev_b32_e32 v170, 16, v160
	v_pk_mul_f32 v[106:107], v[106:107], v[168:169]
	v_lshlrev_b32_e32 v168, 16, v164
	v_and_b32_e32 v164, 0xffff0000, v164
	v_and_b32_e32 v171, 0xffff0000, v160
	v_lshlrev_b32_e32 v160, 16, v165
	v_max_f32_e32 v164, v164, v164
	v_max_f32_e32 v160, v160, v160
	v_max_f32_e32 v164, 0xda24260, v164
	v_max_f32_e32 v160, 0xda24260, v160
	v_rcp_f32_e32 v169, v164
	v_rcp_f32_e32 v164, v160
	v_and_b32_e32 v160, 0xffff0000, v165
	v_max_f32_e32 v160, v160, v160
	v_max_f32_e32 v160, 0xda24260, v160
	v_rcp_f32_e32 v165, v160
	v_lshlrev_b32_e32 v160, 16, v161
	v_and_b32_e32 v161, 0xffff0000, v161
	v_pk_mul_f32 v[176:177], v[176:177], v[178:179]
	v_pk_mul_f32 v[160:161], v[164:165], v[160:161]
	v_lshlrev_b32_e32 v164, 16, v162
	v_pk_mul_f32 v[102:103], v[102:103], v[160:161]
	v_lshlrev_b32_e32 v160, 16, v166
	v_and_b32_e32 v161, 0xffff0000, v166
	v_max_f32_e32 v160, v160, v160
	v_max_f32_e32 v161, v161, v161
	v_max_f32_e32 v160, 0xda24260, v160
	v_max_f32_e32 v161, 0xda24260, v161
	v_rcp_f32_e32 v160, v160
	v_rcp_f32_e32 v161, v161
	v_and_b32_e32 v165, 0xffff0000, v162
	v_lshlrev_b32_e32 v162, 16, v163
	v_and_b32_e32 v163, 0xffff0000, v163
	v_pk_mul_f32 v[160:161], v[160:161], v[164:165]
	v_pk_mul_f32 v[108:109], v[108:109], v[176:177]
	v_pk_mul_f32 v[92:93], v[92:93], v[160:161]
	v_lshlrev_b32_e32 v160, 16, v167
	v_and_b32_e32 v161, 0xffff0000, v167
	v_max_f32_e32 v160, v160, v160
	v_max_f32_e32 v161, v161, v161
	v_max_f32_e32 v160, 0xda24260, v160
	v_max_f32_e32 v161, 0xda24260, v161
	v_rcp_f32_e32 v160, v160
	v_rcp_f32_e32 v161, v161
	v_max_f32_e32 v168, v168, v168
	v_max_f32_e32 v168, 0xda24260, v168
	v_rcp_f32_e32 v168, v168
	v_pk_mul_f32 v[160:161], v[160:161], v[162:163]
	s_waitcnt vmcnt(0)
	v_lshlrev_b32_e32 v162, 16, v152
	v_pk_mul_f32 v[94:95], v[94:95], v[160:161]
	v_lshlrev_b32_e32 v160, 16, v156
	v_and_b32_e32 v156, 0xffff0000, v156
	v_and_b32_e32 v163, 0xffff0000, v152
	v_lshlrev_b32_e32 v152, 16, v157
	v_max_f32_e32 v156, v156, v156
	v_max_f32_e32 v152, v152, v152
	v_max_f32_e32 v156, 0xda24260, v156
	v_max_f32_e32 v152, 0xda24260, v152
	v_rcp_f32_e32 v161, v156
	v_rcp_f32_e32 v156, v152
	v_and_b32_e32 v152, 0xffff0000, v157
	v_max_f32_e32 v152, v152, v152
	v_max_f32_e32 v152, 0xda24260, v152
	v_rcp_f32_e32 v157, v152
	v_lshlrev_b32_e32 v152, 16, v153
	v_and_b32_e32 v153, 0xffff0000, v153
	v_max_f32_e32 v160, v160, v160
	v_pk_mul_f32 v[152:153], v[156:157], v[152:153]
	v_lshlrev_b32_e32 v156, 16, v154
	v_pk_mul_f32 v[98:99], v[98:99], v[152:153]
	v_lshlrev_b32_e32 v152, 16, v158
	v_and_b32_e32 v153, 0xffff0000, v158
	v_max_f32_e32 v152, v152, v152
	v_max_f32_e32 v153, v153, v153
	v_max_f32_e32 v152, 0xda24260, v152
	v_max_f32_e32 v153, 0xda24260, v153
	v_rcp_f32_e32 v152, v152
	v_rcp_f32_e32 v153, v153
	v_and_b32_e32 v157, 0xffff0000, v154
	v_lshlrev_b32_e32 v154, 16, v155
	v_and_b32_e32 v155, 0xffff0000, v155
	v_pk_mul_f32 v[152:153], v[152:153], v[156:157]
	v_max_f32_e32 v160, 0xda24260, v160
	v_pk_mul_f32 v[88:89], v[88:89], v[152:153]
	v_lshlrev_b32_e32 v152, 16, v159
	v_and_b32_e32 v153, 0xffff0000, v159
	v_max_f32_e32 v152, v152, v152
	v_max_f32_e32 v153, v153, v153
	v_max_f32_e32 v152, 0xda24260, v152
	v_max_f32_e32 v153, 0xda24260, v153
	v_rcp_f32_e32 v152, v152
	v_rcp_f32_e32 v153, v153
	v_rcp_f32_e32 v160, v160
	v_pk_mul_f32 v[184:185], v[184:185], v[186:187]
	v_pk_mul_f32 v[168:169], v[168:169], v[170:171]
	v_pk_mul_f32 v[152:153], v[152:153], v[154:155]
	v_lshlrev_b32_e32 v154, 16, v144
	v_pk_mul_f32 v[90:91], v[90:91], v[152:153]
	v_lshlrev_b32_e32 v152, 16, v148
	v_and_b32_e32 v148, 0xffff0000, v148
	v_and_b32_e32 v155, 0xffff0000, v144
	v_lshlrev_b32_e32 v144, 16, v149
	v_max_f32_e32 v148, v148, v148
	v_max_f32_e32 v144, v144, v144
	v_max_f32_e32 v148, 0xda24260, v148
	v_max_f32_e32 v144, 0xda24260, v144
	v_rcp_f32_e32 v153, v148
	v_rcp_f32_e32 v148, v144
	v_and_b32_e32 v144, 0xffff0000, v149
	v_max_f32_e32 v144, v144, v144
	v_max_f32_e32 v144, 0xda24260, v144
	v_rcp_f32_e32 v149, v144
	v_lshlrev_b32_e32 v144, 16, v145
	v_and_b32_e32 v145, 0xffff0000, v145
	v_pk_mul_f32 v[160:161], v[160:161], v[162:163]
	v_pk_mul_f32 v[144:145], v[148:149], v[144:145]
	v_lshlrev_b32_e32 v148, 16, v146
	v_pk_mul_f32 v[86:87], v[86:87], v[144:145]
	v_lshlrev_b32_e32 v144, 16, v150
	v_and_b32_e32 v145, 0xffff0000, v150
	v_max_f32_e32 v144, v144, v144
	v_max_f32_e32 v145, v145, v145
	v_max_f32_e32 v144, 0xda24260, v144
	v_max_f32_e32 v145, 0xda24260, v145
	v_rcp_f32_e32 v144, v144
	v_rcp_f32_e32 v145, v145
	v_and_b32_e32 v149, 0xffff0000, v146
	v_lshlrev_b32_e32 v146, 16, v147
	v_and_b32_e32 v147, 0xffff0000, v147
	v_pk_mul_f32 v[144:145], v[144:145], v[148:149]
	v_pk_mul_f32 v[96:97], v[96:97], v[160:161]
	v_pk_mul_f32 v[76:77], v[76:77], v[144:145]
	v_lshlrev_b32_e32 v144, 16, v151
	v_and_b32_e32 v145, 0xffff0000, v151
	v_max_f32_e32 v144, v144, v144
	v_max_f32_e32 v145, v145, v145
	v_max_f32_e32 v144, 0xda24260, v144
	v_max_f32_e32 v145, 0xda24260, v145
	v_rcp_f32_e32 v144, v144
	v_rcp_f32_e32 v145, v145
	v_pk_mul_f32 v[116:117], v[116:117], v[184:185]
; __device__ __forceinline__ float bf_lo(unsigned u) { return __uint_as_float(u << 16); }
; __device__ __forceinline__ float bf_hi(unsigned u) { return __uint_as_float(u & 0xffff0000u); }
;     __device__ __forceinline__ void mid(f32x4 (&acc)[2][2][4][2], const Unit& u, int wr, int wc, int fr, int fq) const {
;     ...
;             for (int m = 0; m < 4; ++m)
; #pragma unroll
;                 for (int bj = 0; bj < 2; ++bj) { sa[m][bj] = *(const u32x4*)(sg + off + m * 16 * 2048 + bj * HALF); sb[m][bj] = *(const u32x4*)(sg + off + m * 16 * 2048 + 1024 + bj * HALF); }
; #pragma unroll
;             for (int m = 0; m < 4; ++m)
; #pragma unroll
;                 for (int bj = 0; bj < 2; ++bj) {
;                     const unsigned av[4] = {sa[m][bj].x, sa[m][bj].y, sa[m][bj].z, sa[m][bj].w}, bv[4] = {sb[m][bj].x, sb[m][bj].y, sb[m][bj].z, sb[m][bj].w};
; #pragma unroll
;                     for (int q = 0; q < 4; ++q) { const float r0 = bf_lo(av[q]) * __builtin_amdgcn_rcpf(fmaxf(bf_lo(bv[q]), 1e-30f)), r1 = bf_hi(av[q]) * __builtin_amdgcn_rcpf(fmaxf(bf_hi(bv[q]), 1e-30f));
;                         acc[ai][bj][m][q >> 1][(q & 1) * 2] *= r0; acc[ai][bj][m][q >> 1][(q & 1) * 2 + 1] *= r1; } }
;             off += 128u * 2048u; }
	v_pk_mul_f32 v[100:101], v[100:101], v[168:169]
	v_rcp_f32_e32 v238, v219
	v_pk_mul_f32 v[144:145], v[144:145], v[146:147]
	v_lshlrev_b32_e32 v146, 16, v136
	v_pk_mul_f32 v[78:79], v[78:79], v[144:145]
	v_lshlrev_b32_e32 v144, 16, v140
	v_and_b32_e32 v140, 0xffff0000, v140
	v_and_b32_e32 v147, 0xffff0000, v136
	v_lshlrev_b32_e32 v136, 16, v141
	v_max_f32_e32 v140, v140, v140
	v_max_f32_e32 v136, v136, v136
	v_max_f32_e32 v140, 0xda24260, v140
	v_max_f32_e32 v136, 0xda24260, v136
	v_rcp_f32_e32 v145, v140
	v_rcp_f32_e32 v140, v136
	v_and_b32_e32 v136, 0xffff0000, v141
	v_max_f32_e32 v136, v136, v136
	v_max_f32_e32 v136, 0xda24260, v136
	v_rcp_f32_e32 v141, v136
	v_lshlrev_b32_e32 v136, 16, v137
	v_and_b32_e32 v137, 0xffff0000, v137
	v_pk_mul_f32 v[238:239], v[238:239], v[240:241]
	v_pk_mul_f32 v[136:137], v[140:141], v[136:137]
	v_lshlrev_b32_e32 v140, 16, v138
	v_pk_mul_f32 v[82:83], v[82:83], v[136:137]
	v_lshlrev_b32_e32 v136, 16, v142
	v_and_b32_e32 v137, 0xffff0000, v142
	v_max_f32_e32 v136, v136, v136
	v_max_f32_e32 v137, v137, v137
	v_max_f32_e32 v136, 0xda24260, v136
	v_max_f32_e32 v137, 0xda24260, v137
	v_rcp_f32_e32 v136, v136
	v_rcp_f32_e32 v137, v137
	v_and_b32_e32 v141, 0xffff0000, v138
	v_lshlrev_b32_e32 v138, 16, v139
	v_and_b32_e32 v139, 0xffff0000, v139
	v_pk_mul_f32 v[136:137], v[136:137], v[140:141]
	v_pk_mul_f32 v[124:125], v[124:125], v[238:239]
	v_pk_mul_f32 v[72:73], v[72:73], v[136:137]
	v_lshlrev_b32_e32 v136, 16, v143
	v_and_b32_e32 v137, 0xffff0000, v143
	v_max_f32_e32 v136, v136, v136
	v_max_f32_e32 v137, v137, v137
	v_max_f32_e32 v136, 0xda24260, v136
	v_max_f32_e32 v137, 0xda24260, v137
	v_rcp_f32_e32 v136, v136
	v_rcp_f32_e32 v137, v137
	v_max_f32_e32 v152, v152, v152
	v_max_f32_e32 v144, v144, v144
	v_max_f32_e32 v152, 0xda24260, v152
	v_pk_mul_f32 v[136:137], v[136:137], v[138:139]
	v_lshlrev_b32_e32 v138, 16, v128
	v_pk_mul_f32 v[74:75], v[74:75], v[136:137]
	v_lshlrev_b32_e32 v136, 16, v132
	v_and_b32_e32 v132, 0xffff0000, v132
	v_and_b32_e32 v139, 0xffff0000, v128
	v_lshlrev_b32_e32 v128, 16, v133
	v_max_f32_e32 v132, v132, v132
	v_max_f32_e32 v128, v128, v128
	v_max_f32_e32 v132, 0xda24260, v132
	v_max_f32_e32 v128, 0xda24260, v128
	v_rcp_f32_e32 v137, v132
	v_rcp_f32_e32 v132, v128
	v_and_b32_e32 v128, 0xffff0000, v133
	v_max_f32_e32 v128, v128, v128
	v_max_f32_e32 v128, 0xda24260, v128
	v_rcp_f32_e32 v133, v128
	v_lshlrev_b32_e32 v128, 16, v129
	v_and_b32_e32 v129, 0xffff0000, v129
	v_max_f32_e32 v144, 0xda24260, v144
	v_pk_mul_f32 v[128:129], v[132:133], v[128:129]
	v_lshlrev_b32_e32 v132, 16, v130
	v_pk_mul_f32 v[70:71], v[70:71], v[128:129]
	v_lshlrev_b32_e32 v128, 16, v134
	v_and_b32_e32 v129, 0xffff0000, v134
	v_max_f32_e32 v128, v128, v128
	v_max_f32_e32 v129, v129, v129
	v_max_f32_e32 v128, 0xda24260, v128
	v_max_f32_e32 v129, 0xda24260, v129
	v_rcp_f32_e32 v128, v128
	v_rcp_f32_e32 v129, v129
	v_and_b32_e32 v133, 0xffff0000, v130
	v_lshlrev_b32_e32 v130, 16, v131
	v_and_b32_e32 v131, 0xffff0000, v131
	v_pk_mul_f32 v[128:129], v[128:129], v[132:133]
	v_rcp_f32_e32 v152, v152
	v_pk_mul_f32 v[64:65], v[64:65], v[128:129]
	v_lshlrev_b32_e32 v128, 16, v135
	v_and_b32_e32 v129, 0xffff0000, v135
	v_max_f32_e32 v128, v128, v128
	v_max_f32_e32 v129, v129, v129
	v_max_f32_e32 v128, 0xda24260, v128
	v_max_f32_e32 v129, 0xda24260, v129
	v_rcp_f32_e32 v128, v128
	v_rcp_f32_e32 v129, v129
	v_rcp_f32_e32 v144, v144
	v_pk_mul_f32 v[152:153], v[152:153], v[154:155]
	v_max_f32_e32 v136, v136, v136
	v_pk_mul_f32 v[128:129], v[128:129], v[130:131]
	v_pk_mul_f32 v[144:145], v[144:145], v[146:147]
	v_pk_mul_f32 v[66:67], v[66:67], v[128:129]
	v_lshl_add_u64 v[128:129], v[194:195], 1, s[10:11]
	global_load_dwordx4 v[172:175], v[128:129], off
	global_load_dwordx4 v[176:179], v[128:129], off offset:2048
	global_load_dwordx4 v[160:163], v[128:129], off offset:256
	global_load_dwordx4 v[188:191], v[128:129], off offset:2304
	v_add_co_u32_e32 v130, vcc, s72, v128
	v_pk_mul_f32 v[84:85], v[84:85], v[152:153]
	s_nop 0
	v_addc_co_u32_e32 v131, vcc, 0, v129, vcc
	global_load_dwordx4 v[180:183], v[130:131], off
	global_load_dwordx4 v[184:187], v[130:131], off offset:2048
	global_load_dwordx4 v[164:167], v[130:131], off offset:256
	global_load_dwordx4 v[168:171], v[130:131], off offset:2304
	v_add_co_u32_e32 v130, vcc, s43, v128
	v_pk_mul_f32 v[80:81], v[80:81], v[144:145]
	s_nop 0
	v_addc_co_u32_e32 v131, vcc, 0, v129, vcc
	global_load_dwordx4 v[152:155], v[130:131], off
	global_load_dwordx4 v[156:159], v[130:131], off offset:2048
	global_load_dwordx4 v[144:147], v[130:131], off offset:256
	global_load_dwordx4 v[148:151], v[130:131], off offset:2304
	v_max_f32_e32 v136, 0xda24260, v136
	v_rcp_f32_e32 v136, v136
	v_add_co_u32_e32 v132, vcc, s60, v128
	v_pk_mul_f32 v[136:137], v[136:137], v[138:139]
	s_nop 0
	v_addc_co_u32_e32 v133, vcc, 0, v129, vcc
	v_pk_mul_f32 v[68:69], v[68:69], v[136:137]
	global_load_dwordx4 v[136:139], v[132:133], off
	global_load_dwordx4 v[140:143], v[132:133], off offset:2048
	global_load_dwordx4 v[128:131], v[132:133], off offset:256
	s_nop 0
	global_load_dwordx4 v[132:135], v[132:133], off offset:2304
	s_waitcnt vmcnt(0)
; __device__ __forceinline__ float bf_lo(unsigned u) { return __uint_as_float(u << 16); }
; __device__ __forceinline__ float bf_hi(unsigned u) { return __uint_as_float(u & 0xffff0000u); }
;     __device__ __forceinline__ void mid(f32x4 (&acc)[2][2][4][2], const Unit& u, int wr, int wc, int fr, int fq) const {
;     ...
;             for (int m = 0; m < 4; ++m)
; #pragma unroll
;                 for (int bj = 0; bj < 2; ++bj) {
;                     const unsigned av[4] = {sa[m][bj].x, sa[m][bj].y, sa[m][bj].z, sa[m][bj].w}, bv[4] = {sb[m][bj].x, sb[m][bj].y, sb[m][bj].z, sb[m][bj].w};
; #pragma unroll
;                     for (int q = 0; q < 4; ++q) { const float r0 = bf_lo(av[q]) * __builtin_amdgcn_rcpf(fmaxf(bf_lo(bv[q]), 1e-30f)), r1 = bf_hi(av[q]) * __builtin_amdgcn_rcpf(fmaxf(bf_hi(bv[q]), 1e-30f));
;                         acc[ai][bj][m][q >> 1][(q & 1) * 2] *= r0; acc[ai][bj][m][q >> 1][(q & 1) * 2 + 1] *= r1; } }
;             off += 128u * 2048u; }
	v_lshlrev_b32_e32 v240, 16, v172
	v_lshlrev_b32_e32 v194, 16, v176
	v_and_b32_e32 v176, 0xffff0000, v176
	v_and_b32_e32 v241, 0xffff0000, v172
	v_lshlrev_b32_e32 v172, 16, v177
	v_max_f32_e32 v176, v176, v176
	v_max_f32_e32 v172, v172, v172
	v_max_f32_e32 v176, 0xda24260, v176
	v_max_f32_e32 v172, 0xda24260, v172
	v_rcp_f32_e32 v239, v176
	v_rcp_f32_e32 v176, v172
	v_and_b32_e32 v172, 0xffff0000, v177
	v_max_f32_e32 v172, v172, v172
	v_max_f32_e32 v172, 0xda24260, v172
	v_rcp_f32_e32 v177, v172
	v_lshlrev_b32_e32 v172, 16, v173
	v_and_b32_e32 v173, 0xffff0000, v173
	v_max_f32_e32 v194, v194, v194
	v_pk_mul_f32 v[172:173], v[176:177], v[172:173]
	v_lshlrev_b32_e32 v176, 16, v174
	v_pk_mul_f32 v[62:63], v[62:63], v[172:173]
	v_lshlrev_b32_e32 v172, 16, v178
	v_and_b32_e32 v173, 0xffff0000, v178
	v_max_f32_e32 v172, v172, v172
	v_max_f32_e32 v173, v173, v173
	v_max_f32_e32 v172, 0xda24260, v172
	v_max_f32_e32 v173, 0xda24260, v173
	v_rcp_f32_e32 v172, v172
	v_rcp_f32_e32 v173, v173
	v_and_b32_e32 v177, 0xffff0000, v174
	v_lshlrev_b32_e32 v174, 16, v175
	v_and_b32_e32 v175, 0xffff0000, v175
	v_pk_mul_f32 v[172:173], v[172:173], v[176:177]
	v_max_f32_e32 v194, 0xda24260, v194
	v_pk_mul_f32 v[56:57], v[56:57], v[172:173]
	v_lshlrev_b32_e32 v172, 16, v179
	v_and_b32_e32 v173, 0xffff0000, v179
	v_max_f32_e32 v172, v172, v172
	v_max_f32_e32 v173, v173, v173
	v_max_f32_e32 v172, 0xda24260, v172
	v_max_f32_e32 v173, 0xda24260, v173
	v_rcp_f32_e32 v172, v172
	v_rcp_f32_e32 v173, v173
	v_rcp_f32_e32 v238, v194
	v_pk_mul_f32 v[172:173], v[172:173], v[174:175]
	s_nop 0
	v_pk_mul_f32 v[58:59], v[58:59], v[172:173]
	v_lshlrev_b32_e32 v172, 16, v188
	v_and_b32_e32 v173, 0xffff0000, v188
	v_max_f32_e32 v172, v172, v172
	v_max_f32_e32 v173, v173, v173
	v_max_f32_e32 v172, 0xda24260, v172
	v_max_f32_e32 v173, 0xda24260, v173
	v_rcp_f32_e32 v172, v172
	v_rcp_f32_e32 v173, v173
	v_lshlrev_b32_e32 v174, 16, v160
	v_and_b32_e32 v175, 0xffff0000, v160
	v_lshlrev_b32_e32 v160, 16, v189
	v_max_f32_e32 v160, v160, v160
	v_pk_mul_f32 v[172:173], v[172:173], v[174:175]
	v_max_f32_e32 v160, 0xda24260, v160
	v_pk_mul_f32 v[52:53], v[52:53], v[172:173]
	v_rcp_f32_e32 v172, v160
	v_and_b32_e32 v160, 0xffff0000, v189
	v_max_f32_e32 v160, v160, v160
	v_max_f32_e32 v160, 0xda24260, v160
	v_rcp_f32_e32 v173, v160
	v_lshlrev_b32_e32 v160, 16, v161
	v_and_b32_e32 v161, 0xffff0000, v161
	v_pk_mul_f32 v[238:239], v[238:239], v[240:241]
	v_pk_mul_f32 v[160:161], v[172:173], v[160:161]
	v_lshlrev_b32_e32 v172, 16, v162
	v_pk_mul_f32 v[54:55], v[54:55], v[160:161]
	v_lshlrev_b32_e32 v160, 16, v190
	v_and_b32_e32 v161, 0xffff0000, v190
	v_max_f32_e32 v160, v160, v160
	v_max_f32_e32 v161, v161, v161
	v_max_f32_e32 v160, 0xda24260, v160
	v_max_f32_e32 v161, 0xda24260, v161
	v_rcp_f32_e32 v160, v160
	v_rcp_f32_e32 v161, v161
	v_and_b32_e32 v173, 0xffff0000, v162
	v_lshlrev_b32_e32 v162, 16, v163
	v_and_b32_e32 v163, 0xffff0000, v163
	v_pk_mul_f32 v[160:161], v[160:161], v[172:173]
	v_pk_mul_f32 v[60:61], v[60:61], v[238:239]
	v_pk_mul_f32 v[44:45], v[44:45], v[160:161]
	v_lshlrev_b32_e32 v160, 16, v191
	v_and_b32_e32 v161, 0xffff0000, v191
	v_max_f32_e32 v160, v160, v160
	v_max_f32_e32 v161, v161, v161
	v_max_f32_e32 v160, 0xda24260, v160
	v_max_f32_e32 v161, 0xda24260, v161
	v_rcp_f32_e32 v160, v160
	v_rcp_f32_e32 v161, v161
	s_nop 0
	v_pk_mul_f32 v[160:161], v[160:161], v[162:163]
	s_nop 0
	v_pk_mul_f32 v[46:47], v[46:47], v[160:161]
	v_lshlrev_b32_e32 v160, 16, v184
	v_and_b32_e32 v161, 0xffff0000, v184
	v_max_f32_e32 v160, v160, v160
	v_max_f32_e32 v161, v161, v161
	v_max_f32_e32 v160, 0xda24260, v160
	v_max_f32_e32 v161, 0xda24260, v161
	v_rcp_f32_e32 v160, v160
	v_rcp_f32_e32 v161, v161
	v_lshlrev_b32_e32 v162, 16, v180
	v_and_b32_e32 v163, 0xffff0000, v180
	v_pk_mul_f32 v[160:161], v[160:161], v[162:163]
	s_nop 0
	v_pk_mul_f32 v[48:49], v[48:49], v[160:161]
	v_lshlrev_b32_e32 v160, 16, v185
	v_and_b32_e32 v161, 0xffff0000, v185
	v_max_f32_e32 v160, v160, v160
	v_max_f32_e32 v161, v161, v161
	v_max_f32_e32 v160, 0xda24260, v160
	v_max_f32_e32 v161, 0xda24260, v161
	v_rcp_f32_e32 v160, v160
	v_rcp_f32_e32 v161, v161
	v_lshlrev_b32_e32 v162, 16, v181
	v_and_b32_e32 v163, 0xffff0000, v181
	v_pk_mul_f32 v[160:161], v[160:161], v[162:163]
	s_nop 0
	v_pk_mul_f32 v[50:51], v[50:51], v[160:161]
	v_lshlrev_b32_e32 v160, 16, v186
	v_and_b32_e32 v161, 0xffff0000, v186
	v_max_f32_e32 v160, v160, v160
	v_max_f32_e32 v161, v161, v161
	v_max_f32_e32 v160, 0xda24260, v160
	v_max_f32_e32 v161, 0xda24260, v161
	v_rcp_f32_e32 v160, v160
	v_rcp_f32_e32 v161, v161
	v_lshlrev_b32_e32 v162, 16, v182
	v_and_b32_e32 v163, 0xffff0000, v182
	v_pk_mul_f32 v[160:161], v[160:161], v[162:163]
	s_nop 0
	v_pk_mul_f32 v[40:41], v[40:41], v[160:161]
	v_lshlrev_b32_e32 v160, 16, v187
	v_and_b32_e32 v161, 0xffff0000, v187
	v_max_f32_e32 v160, v160, v160
	v_max_f32_e32 v161, v161, v161
	v_max_f32_e32 v160, 0xda24260, v160
	v_max_f32_e32 v161, 0xda24260, v161
	v_rcp_f32_e32 v160, v160
	v_rcp_f32_e32 v161, v161
	v_lshlrev_b32_e32 v162, 16, v183
	v_and_b32_e32 v163, 0xffff0000, v183
	v_pk_mul_f32 v[160:161], v[160:161], v[162:163]
	s_nop 0
	v_pk_mul_f32 v[42:43], v[42:43], v[160:161]
	v_lshlrev_b32_e32 v160, 16, v168
	v_and_b32_e32 v161, 0xffff0000, v168
	v_max_f32_e32 v160, v160, v160
	v_max_f32_e32 v161, v161, v161
	v_max_f32_e32 v160, 0xda24260, v160
	v_max_f32_e32 v161, 0xda24260, v161
	v_rcp_f32_e32 v160, v160
	v_rcp_f32_e32 v161, v161
	v_lshlrev_b32_e32 v162, 16, v164
	v_and_b32_e32 v163, 0xffff0000, v164
	v_pk_mul_f32 v[160:161], v[160:161], v[162:163]
	s_nop 0
	v_pk_mul_f32 v[36:37], v[36:37], v[160:161]
; __device__ __forceinline__ float bf_lo(unsigned u) { return __uint_as_float(u << 16); }
; __device__ __forceinline__ float bf_hi(unsigned u) { return __uint_as_float(u & 0xffff0000u); }
;     __device__ __forceinline__ void mid(f32x4 (&acc)[2][2][4][2], const Unit& u, int wr, int wc, int fr, int fq) const {
;     ...
;             for (int m = 0; m < 4; ++m)
; #pragma unroll
;                 for (int bj = 0; bj < 2; ++bj) {
;                     const unsigned av[4] = {sa[m][bj].x, sa[m][bj].y, sa[m][bj].z, sa[m][bj].w}, bv[4] = {sb[m][bj].x, sb[m][bj].y, sb[m][bj].z, sb[m][bj].w};
; #pragma unroll
;                     for (int q = 0; q < 4; ++q) { const float r0 = bf_lo(av[q]) * __builtin_amdgcn_rcpf(fmaxf(bf_lo(bv[q]), 1e-30f)), r1 = bf_hi(av[q]) * __builtin_amdgcn_rcpf(fmaxf(bf_hi(bv[q]), 1e-30f));
;                         acc[ai][bj][m][q >> 1][(q & 1) * 2] *= r0; acc[ai][bj][m][q >> 1][(q & 1) * 2 + 1] *= r1; } }
;             off += 128u * 2048u; }
	v_lshlrev_b32_e32 v160, 16, v169
	v_and_b32_e32 v161, 0xffff0000, v169
	v_max_f32_e32 v160, v160, v160
	v_max_f32_e32 v161, v161, v161
	v_max_f32_e32 v160, 0xda24260, v160
	v_max_f32_e32 v161, 0xda24260, v161
	v_rcp_f32_e32 v160, v160
	v_rcp_f32_e32 v161, v161
	v_lshlrev_b32_e32 v162, 16, v165
	v_and_b32_e32 v163, 0xffff0000, v165
	v_pk_mul_f32 v[160:161], v[160:161], v[162:163]
	s_nop 0
	v_pk_mul_f32 v[38:39], v[38:39], v[160:161]
	v_lshlrev_b32_e32 v160, 16, v170
	v_and_b32_e32 v161, 0xffff0000, v170
	v_max_f32_e32 v160, v160, v160
	v_max_f32_e32 v161, v161, v161
	v_max_f32_e32 v160, 0xda24260, v160
	v_max_f32_e32 v161, 0xda24260, v161
	v_rcp_f32_e32 v160, v160
	v_rcp_f32_e32 v161, v161
	v_lshlrev_b32_e32 v162, 16, v166
	v_and_b32_e32 v163, 0xffff0000, v166
	v_pk_mul_f32 v[160:161], v[160:161], v[162:163]
	s_nop 0
	v_pk_mul_f32 v[28:29], v[28:29], v[160:161]
	v_lshlrev_b32_e32 v160, 16, v171
	v_and_b32_e32 v161, 0xffff0000, v171
	v_max_f32_e32 v160, v160, v160
	v_max_f32_e32 v161, v161, v161
	v_max_f32_e32 v160, 0xda24260, v160
	v_max_f32_e32 v161, 0xda24260, v161
	v_rcp_f32_e32 v160, v160
	v_rcp_f32_e32 v161, v161
	v_lshlrev_b32_e32 v162, 16, v167
	v_and_b32_e32 v163, 0xffff0000, v167
	v_pk_mul_f32 v[160:161], v[160:161], v[162:163]
	s_nop 0
	v_pk_mul_f32 v[30:31], v[30:31], v[160:161]
	v_lshlrev_b32_e32 v160, 16, v156
	v_and_b32_e32 v156, 0xffff0000, v156
	v_lshlrev_b32_e32 v162, 16, v152
	v_and_b32_e32 v163, 0xffff0000, v152
	v_lshlrev_b32_e32 v152, 16, v157
	v_max_f32_e32 v156, v156, v156
	v_max_f32_e32 v152, v152, v152
	v_max_f32_e32 v156, 0xda24260, v156
	v_max_f32_e32 v152, 0xda24260, v152
	v_rcp_f32_e32 v161, v156
	v_rcp_f32_e32 v156, v152
	v_and_b32_e32 v152, 0xffff0000, v157
	v_max_f32_e32 v152, v152, v152
	v_max_f32_e32 v152, 0xda24260, v152
	v_rcp_f32_e32 v157, v152
	v_lshlrev_b32_e32 v152, 16, v153
	v_and_b32_e32 v153, 0xffff0000, v153
	v_max_f32_e32 v160, v160, v160
	v_pk_mul_f32 v[152:153], v[156:157], v[152:153]
	v_lshlrev_b32_e32 v156, 16, v154
	v_pk_mul_f32 v[34:35], v[34:35], v[152:153]
	v_lshlrev_b32_e32 v152, 16, v158
	v_and_b32_e32 v153, 0xffff0000, v158
	v_max_f32_e32 v152, v152, v152
	v_max_f32_e32 v153, v153, v153
	v_max_f32_e32 v152, 0xda24260, v152
	v_max_f32_e32 v153, 0xda24260, v153
	v_rcp_f32_e32 v152, v152
	v_rcp_f32_e32 v153, v153
	v_and_b32_e32 v157, 0xffff0000, v154
	v_lshlrev_b32_e32 v154, 16, v155
	v_and_b32_e32 v155, 0xffff0000, v155
	v_pk_mul_f32 v[152:153], v[152:153], v[156:157]
	v_max_f32_e32 v160, 0xda24260, v160
	v_pk_mul_f32 v[24:25], v[24:25], v[152:153]
	v_lshlrev_b32_e32 v152, 16, v159
	v_and_b32_e32 v153, 0xffff0000, v159
	v_max_f32_e32 v152, v152, v152
	v_max_f32_e32 v153, v153, v153
	v_max_f32_e32 v152, 0xda24260, v152
	v_max_f32_e32 v153, 0xda24260, v153
	v_rcp_f32_e32 v152, v152
	v_rcp_f32_e32 v153, v153
	v_rcp_f32_e32 v160, v160
	v_pk_mul_f32 v[152:153], v[152:153], v[154:155]
	s_nop 0
	v_pk_mul_f32 v[26:27], v[26:27], v[152:153]
	v_lshlrev_b32_e32 v152, 16, v148
	v_and_b32_e32 v148, 0xffff0000, v148
	v_lshlrev_b32_e32 v154, 16, v144
	v_and_b32_e32 v155, 0xffff0000, v144
	v_lshlrev_b32_e32 v144, 16, v149
	v_max_f32_e32 v148, v148, v148
	v_max_f32_e32 v144, v144, v144
	v_max_f32_e32 v148, 0xda24260, v148
	v_max_f32_e32 v144, 0xda24260, v144
	v_rcp_f32_e32 v153, v148
	v_rcp_f32_e32 v148, v144
	v_and_b32_e32 v144, 0xffff0000, v149
	v_max_f32_e32 v144, v144, v144
	v_max_f32_e32 v144, 0xda24260, v144
	v_rcp_f32_e32 v149, v144
	v_lshlrev_b32_e32 v144, 16, v145
	v_and_b32_e32 v145, 0xffff0000, v145
	v_max_f32_e32 v152, v152, v152
	v_pk_mul_f32 v[144:145], v[148:149], v[144:145]
	v_lshlrev_b32_e32 v148, 16, v146
	v_pk_mul_f32 v[22:23], v[22:23], v[144:145]
	v_lshlrev_b32_e32 v144, 16, v150
	v_and_b32_e32 v145, 0xffff0000, v150
	v_max_f32_e32 v144, v144, v144
	v_max_f32_e32 v145, v145, v145
	v_max_f32_e32 v144, 0xda24260, v144
	v_max_f32_e32 v145, 0xda24260, v145
	v_rcp_f32_e32 v144, v144
	v_rcp_f32_e32 v145, v145
	v_and_b32_e32 v149, 0xffff0000, v146
	v_lshlrev_b32_e32 v146, 16, v147
	v_and_b32_e32 v147, 0xffff0000, v147
	v_pk_mul_f32 v[144:145], v[144:145], v[148:149]
; __device__ __forceinline__ float bf_lo(unsigned u) { return __uint_as_float(u << 16); }
; __device__ __forceinline__ float bf_hi(unsigned u) { return __uint_as_float(u & 0xffff0000u); }
;     __device__ __forceinline__ void mid(f32x4 (&acc)[2][2][4][2], const Unit& u, int wr, int wc, int fr, int fq) const {
;     ...
;             for (int m = 0; m < 4; ++m)
; #pragma unroll
;                 for (int bj = 0; bj < 2; ++bj) {
;                     const unsigned av[4] = {sa[m][bj].x, sa[m][bj].y, sa[m][bj].z, sa[m][bj].w}, bv[4] = {sb[m][bj].x, sb[m][bj].y, sb[m][bj].z, sb[m][bj].w};
; #pragma unroll
;                     for (int q = 0; q < 4; ++q) { const float r0 = bf_lo(av[q]) * __builtin_amdgcn_rcpf(fmaxf(bf_lo(bv[q]), 1e-30f)), r1 = bf_hi(av[q]) * __builtin_amdgcn_rcpf(fmaxf(bf_hi(bv[q]), 1e-30f));
;                         acc[ai][bj][m][q >> 1][(q & 1) * 2] *= r0; acc[ai][bj][m][q >> 1][(q & 1) * 2 + 1] *= r1; } }
;             off += 128u * 2048u; }
	v_max_f32_e32 v152, 0xda24260, v152
	v_pk_mul_f32 v[12:13], v[12:13], v[144:145]
	v_lshlrev_b32_e32 v144, 16, v151
	v_and_b32_e32 v145, 0xffff0000, v151
	v_max_f32_e32 v144, v144, v144
	v_max_f32_e32 v145, v145, v145
	v_max_f32_e32 v144, 0xda24260, v144
	v_max_f32_e32 v145, 0xda24260, v145
	v_rcp_f32_e32 v144, v144
	v_rcp_f32_e32 v145, v145
	v_rcp_f32_e32 v152, v152
	v_pk_mul_f32 v[160:161], v[160:161], v[162:163]
	v_pk_mul_f32 v[144:145], v[144:145], v[146:147]
	s_nop 0
	v_pk_mul_f32 v[14:15], v[14:15], v[144:145]
	v_lshlrev_b32_e32 v144, 16, v140
	v_and_b32_e32 v140, 0xffff0000, v140
	v_lshlrev_b32_e32 v146, 16, v136
	v_and_b32_e32 v147, 0xffff0000, v136
	v_lshlrev_b32_e32 v136, 16, v141
	v_max_f32_e32 v140, v140, v140
	v_max_f32_e32 v136, v136, v136
	v_max_f32_e32 v140, 0xda24260, v140
	v_max_f32_e32 v136, 0xda24260, v136
	v_rcp_f32_e32 v145, v140
	v_rcp_f32_e32 v140, v136
	v_and_b32_e32 v136, 0xffff0000, v141
	v_max_f32_e32 v136, v136, v136
	v_max_f32_e32 v136, 0xda24260, v136
	v_rcp_f32_e32 v141, v136
	v_lshlrev_b32_e32 v136, 16, v137
	v_and_b32_e32 v137, 0xffff0000, v137
	v_max_f32_e32 v144, v144, v144
	v_pk_mul_f32 v[136:137], v[140:141], v[136:137]
	v_lshlrev_b32_e32 v140, 16, v138
	v_pk_mul_f32 v[18:19], v[18:19], v[136:137]
	v_lshlrev_b32_e32 v136, 16, v142
	v_and_b32_e32 v137, 0xffff0000, v142
	v_max_f32_e32 v136, v136, v136
	v_max_f32_e32 v137, v137, v137
	v_max_f32_e32 v136, 0xda24260, v136
	v_max_f32_e32 v137, 0xda24260, v137
	v_rcp_f32_e32 v136, v136
	v_rcp_f32_e32 v137, v137
	v_and_b32_e32 v141, 0xffff0000, v138
	v_lshlrev_b32_e32 v138, 16, v139
	v_and_b32_e32 v139, 0xffff0000, v139
	v_pk_mul_f32 v[136:137], v[136:137], v[140:141]
	v_max_f32_e32 v144, 0xda24260, v144
	v_pk_mul_f32 v[8:9], v[8:9], v[136:137]
	v_lshlrev_b32_e32 v136, 16, v143
	v_and_b32_e32 v137, 0xffff0000, v143
	v_max_f32_e32 v136, v136, v136
	v_max_f32_e32 v137, v137, v137
	v_max_f32_e32 v136, 0xda24260, v136
	v_max_f32_e32 v137, 0xda24260, v137
	v_rcp_f32_e32 v136, v136
	v_rcp_f32_e32 v137, v137
	v_rcp_f32_e32 v144, v144
	v_pk_mul_f32 v[152:153], v[152:153], v[154:155]
	v_pk_mul_f32 v[32:33], v[32:33], v[160:161]
	v_pk_mul_f32 v[136:137], v[136:137], v[138:139]
	v_lshlrev_b32_e32 v138, 16, v128
	v_pk_mul_f32 v[10:11], v[10:11], v[136:137]
	v_lshlrev_b32_e32 v136, 16, v132
	v_and_b32_e32 v132, 0xffff0000, v132
	v_and_b32_e32 v139, 0xffff0000, v128
	v_lshlrev_b32_e32 v128, 16, v133
	v_max_f32_e32 v132, v132, v132
	v_max_f32_e32 v128, v128, v128
	v_max_f32_e32 v132, 0xda24260, v132
	v_max_f32_e32 v128, 0xda24260, v128
	v_rcp_f32_e32 v137, v132
	v_rcp_f32_e32 v132, v128
	v_and_b32_e32 v128, 0xffff0000, v133
	v_max_f32_e32 v128, v128, v128
	v_max_f32_e32 v128, 0xda24260, v128
	v_rcp_f32_e32 v133, v128
	v_lshlrev_b32_e32 v128, 16, v129
	v_and_b32_e32 v129, 0xffff0000, v129
	v_max_f32_e32 v136, v136, v136
	v_pk_mul_f32 v[128:129], v[132:133], v[128:129]
	v_lshlrev_b32_e32 v132, 16, v130
	v_pk_mul_f32 v[6:7], v[6:7], v[128:129]
	v_lshlrev_b32_e32 v128, 16, v134
	v_and_b32_e32 v129, 0xffff0000, v134
	v_max_f32_e32 v128, v128, v128
	v_max_f32_e32 v129, v129, v129
	v_max_f32_e32 v128, 0xda24260, v128
	v_max_f32_e32 v129, 0xda24260, v129
	v_rcp_f32_e32 v128, v128
	v_rcp_f32_e32 v129, v129
	v_and_b32_e32 v133, 0xffff0000, v130
	v_max_f32_e32 v136, 0xda24260, v136
	v_rcp_f32_e32 v136, v136
	v_pk_mul_f32 v[128:129], v[128:129], v[132:133]
	v_lshlrev_b32_e32 v130, 16, v131
	v_pk_mul_f32 v[0:1], v[0:1], v[128:129]
	v_lshlrev_b32_e32 v128, 16, v135
	v_and_b32_e32 v129, 0xffff0000, v135
	v_max_f32_e32 v128, v128, v128
	v_max_f32_e32 v129, v129, v129
	v_max_f32_e32 v128, 0xda24260, v128
	v_max_f32_e32 v129, 0xda24260, v129
	v_rcp_f32_e32 v128, v128
	v_rcp_f32_e32 v129, v129
	v_and_b32_e32 v131, 0xffff0000, v131
	v_pk_mul_f32 v[144:145], v[144:145], v[146:147]
	v_pk_mul_f32 v[136:137], v[136:137], v[138:139]
	v_pk_mul_f32 v[128:129], v[128:129], v[130:131]
	v_pk_mul_f32 v[20:21], v[20:21], v[152:153]
	v_pk_mul_f32 v[16:17], v[16:17], v[144:145]
	v_pk_mul_f32 v[4:5], v[4:5], v[136:137]
	v_pk_mul_f32 v[2:3], v[2:3], v[128:129]
	s_branch .LBB0_422

; __device__ __forceinline__ unsigned cvt_pk_bf16(float lo, float hi) { unsigned r; asm volatile("v_cvt_pk_bf16_f32 %0, %1, %2" : "=v"(r) : "v"(lo), "v"(hi)); return r; }
; __device__ __forceinline__ float bf_lo(unsigned u) { return __uint_as_float(u << 16); }
; __device__ __forceinline__ float bf_hi(unsigned u) { return __uint_as_float(u & 0xffff0000u); }
;     __device__ __forceinline__ void operator()(const f32x4 (&acc)[2][2][4][2], const Unit& u, int wr, int wc, int fr, int fq) const {
;     ...
;             u32x4 sb[4][2];
; #pragma unroll
;             for (int m = 0; m < 4; ++m)
; #pragma unroll
;                 for (int bj = 0; bj < 2; ++bj) sb[m][bj] = *(const u32x4*)(sg + off + m * 16 * 2048 + 1024 + bj * HALF);
;             const unsigned mo = (off >> 11) * 1024u + (off & 2047u);
; #pragma unroll
;             for (int m = 0; m < 4; ++m)
; #pragma unroll
;                 for (int bj = 0; bj < 2; ++bj) { const u32x4 s = sb[m][bj];
;                     const f32x4 a0 = acc[ai][bj][m][0], a1 = acc[ai][bj][m][1];
;                     u32x4 w; w.x = cvt_pk_bf16(a0[0] * bf_lo(s.x), a0[1] * bf_hi(s.x)); w.y = cvt_pk_bf16(a0[2] * bf_lo(s.y), a0[3] * bf_hi(s.y));
;                     w.z = cvt_pk_bf16(a1[0] * bf_lo(s.z), a1[1] * bf_hi(s.z)); w.w = cvt_pk_bf16(a1[2] * bf_lo(s.w), a1[3] * bf_hi(s.w));
;                     *(u32x4*)(merged + mo + m * 16 * 1024 + bj * HALF) = w; }
.LBB0_427:
	v_mov_b32_e32 v219, v195
	s_mov_b32 s1, 0x8000
	v_lshl_add_u64 v[128:129], v[218:219], 1, s[10:11]
	global_load_dwordx4 v[156:159], v[128:129], off offset:2048
	global_load_dwordx4 v[152:155], v[128:129], off offset:2304
	v_add_co_u32_e32 v130, vcc, 0x10000, v128
	v_lshrrev_b32_e32 v160, 1, v218
	s_nop 0
	v_addc_co_u32_e32 v131, vcc, 0, v129, vcc
	global_load_dwordx4 v[148:151], v[130:131], off offset:2048
	global_load_dwordx4 v[144:147], v[130:131], off offset:2304
	v_add_co_u32_e32 v130, vcc, 0x20000, v128
	v_and_b32_e32 v160, 0x7ffffc00, v160
	s_nop 0
	v_addc_co_u32_e32 v131, vcc, 0, v129, vcc
	global_load_dwordx4 v[140:143], v[130:131], off offset:2048
	global_load_dwordx4 v[136:139], v[130:131], off offset:2304
	v_add_co_u32_e32 v128, vcc, 0x30000, v128
	v_and_b32_e32 v161, 0x7ff, v218
	s_nop 0
	v_addc_co_u32_e32 v129, vcc, 0, v129, vcc
	global_load_dwordx4 v[132:135], v[128:129], off offset:2048
	s_nop 0
	global_load_dwordx4 v[128:131], v[128:129], off offset:2304
	v_add_u32_e32 v194, v160, v161
	v_add_u32_e32 v190, 0x40000, v218
	v_mov_b32_e32 v191, 0
	v_lshl_add_u64 v[184:185], v[190:191], 1, s[10:11]
	global_load_dwordx4 v[160:163], v[184:185], off offset:2048
	global_load_dwordx4 v[164:167], v[184:185], off offset:2304
	v_add_co_u32_e32 v172, vcc, s72, v184
	s_nop 1
	v_addc_co_u32_e32 v173, vcc, 0, v185, vcc
	global_load_dwordx4 v[168:171], v[172:173], off offset:2048
	s_nop 0
	global_load_dwordx4 v[172:175], v[172:173], off offset:2304
	v_add_co_u32_e32 v180, vcc, s43, v184
	s_nop 1
	v_addc_co_u32_e32 v181, vcc, 0, v185, vcc
	global_load_dwordx4 v[176:179], v[180:181], off offset:2048
	s_nop 0
	global_load_dwordx4 v[180:183], v[180:181], off offset:2304
	v_add_co_u32_e32 v188, vcc, s60, v184
	s_nop 1
	v_addc_co_u32_e32 v189, vcc, 0, v185, vcc
	global_load_dwordx4 v[184:187], v[188:189], off offset:2048
	s_nop 0
	global_load_dwordx4 v[188:191], v[188:189], off offset:2304
	s_mov_b32 s0, 0x18000
	s_waitcnt vmcnt(0)
	v_lshlrev_b32_e32 v219, 16, v156
	v_and_b32_e32 v156, 0xffff0000, v156
	v_mul_f32_e32 v124, v124, v219
	v_mul_f32_e32 v125, v125, v156
	v_cvt_pk_bf16_f32 v124, v124, v125
	v_lshlrev_b32_e32 v125, 16, v157
	v_mul_f32_e32 v125, v126, v125
	v_and_b32_e32 v126, 0xffff0000, v157
	v_mul_f32_e32 v126, v127, v126
	v_cvt_pk_bf16_f32 v125, v125, v126
	v_lshlrev_b32_e32 v126, 16, v158
	v_mul_f32_e32 v120, v120, v126
	v_and_b32_e32 v126, 0xffff0000, v158
	v_mul_f32_e32 v121, v121, v126
	v_cvt_pk_bf16_f32 v126, v120, v121
	v_lshlrev_b32_e32 v120, 16, v159
	v_mul_f32_e32 v120, v122, v120
	v_and_b32_e32 v121, 0xffff0000, v159
	v_lshlrev_b32_e32 v122, 16, v152
	v_mul_f32_e32 v121, v123, v121
	v_mul_f32_e32 v116, v116, v122
	v_and_b32_e32 v122, 0xffff0000, v152
	v_cvt_pk_bf16_f32 v127, v120, v121
	v_lshl_add_u64 v[120:121], v[194:195], 1, s[12:13]
	v_mul_f32_e32 v117, v117, v122
	global_store_dwordx4 v[120:121], v[124:127], off
	v_cvt_pk_bf16_f32 v116, v116, v117
	v_lshlrev_b32_e32 v117, 16, v153
	v_mul_f32_e32 v117, v118, v117
	v_and_b32_e32 v118, 0xffff0000, v153
	v_mul_f32_e32 v118, v119, v118
	v_cvt_pk_bf16_f32 v117, v117, v118
	v_lshlrev_b32_e32 v118, 16, v154
	v_mul_f32_e32 v112, v112, v118
	v_and_b32_e32 v118, 0xffff0000, v154
	v_mul_f32_e32 v113, v113, v118
	v_cvt_pk_bf16_f32 v118, v112, v113
	v_lshlrev_b32_e32 v112, 16, v155
	v_mul_f32_e32 v112, v114, v112
	v_and_b32_e32 v113, 0xffff0000, v155
	v_mul_f32_e32 v113, v115, v113
	v_cvt_pk_bf16_f32 v119, v112, v113
	v_lshlrev_b32_e32 v112, 16, v148
	v_mul_f32_e32 v108, v108, v112
	v_and_b32_e32 v112, 0xffff0000, v148
	v_mul_f32_e32 v109, v109, v112
	global_store_dwordx4 v[120:121], v[116:119], off offset:256
	v_cvt_pk_bf16_f32 v108, v108, v109
	v_lshlrev_b32_e32 v109, 16, v149
	v_mul_f32_e32 v109, v110, v109
	v_and_b32_e32 v110, 0xffff0000, v149
	v_mul_f32_e32 v110, v111, v110
	v_cvt_pk_bf16_f32 v109, v109, v110
	v_lshlrev_b32_e32 v110, 16, v150
	v_mul_f32_e32 v104, v104, v110
	v_and_b32_e32 v110, 0xffff0000, v150
	v_mul_f32_e32 v105, v105, v110
	v_cvt_pk_bf16_f32 v110, v104, v105
	v_lshlrev_b32_e32 v104, 16, v151
	v_mul_f32_e32 v104, v106, v104
	v_and_b32_e32 v105, 0xffff0000, v151
	v_lshlrev_b32_e32 v106, 16, v144
	v_mul_f32_e32 v105, v107, v105
	v_cvt_pk_bf16_f32 v111, v104, v105
	v_add_co_u32_e32 v104, vcc, s1, v120
	v_mul_f32_e32 v100, v100, v106
	v_and_b32_e32 v106, 0xffff0000, v144
	v_addc_co_u32_e32 v105, vcc, 0, v121, vcc
	v_mul_f32_e32 v101, v101, v106
	global_store_dwordx4 v[104:105], v[108:111], off
	v_cvt_pk_bf16_f32 v100, v100, v101
	v_lshlrev_b32_e32 v101, 16, v145
	v_mul_f32_e32 v101, v102, v101
	v_and_b32_e32 v102, 0xffff0000, v145
	v_mul_f32_e32 v102, v103, v102
	v_cvt_pk_bf16_f32 v101, v101, v102
	v_lshlrev_b32_e32 v102, 16, v146
	v_mul_f32_e32 v92, v92, v102
	v_and_b32_e32 v102, 0xffff0000, v146
	v_mul_f32_e32 v93, v93, v102
	v_cvt_pk_bf16_f32 v102, v92, v93
	v_lshlrev_b32_e32 v92, 16, v147
	v_and_b32_e32 v93, 0xffff0000, v147
	v_mul_f32_e32 v92, v94, v92
	v_mul_f32_e32 v93, v95, v93
	v_cvt_pk_bf16_f32 v103, v92, v93
	v_lshlrev_b32_e32 v92, 16, v140
	v_and_b32_e32 v93, 0xffff0000, v140
	v_mul_f32_e32 v92, v96, v92
	v_mul_f32_e32 v93, v97, v93
	global_store_dwordx4 v[104:105], v[100:103], off offset:256
	v_cvt_pk_bf16_f32 v92, v92, v93
	v_lshlrev_b32_e32 v93, 16, v141
	v_and_b32_e32 v94, 0xffff0000, v141
	v_mul_f32_e32 v93, v98, v93
	v_mul_f32_e32 v94, v99, v94
	v_cvt_pk_bf16_f32 v93, v93, v94
	v_lshlrev_b32_e32 v94, 16, v142
	v_mul_f32_e32 v88, v88, v94
	v_and_b32_e32 v94, 0xffff0000, v142
	v_mul_f32_e32 v89, v89, v94
	v_cvt_pk_bf16_f32 v94, v88, v89
	v_lshlrev_b32_e32 v88, 16, v143
	v_mul_f32_e32 v88, v90, v88
	v_and_b32_e32 v89, 0xffff0000, v143
; __device__ __forceinline__ unsigned cvt_pk_bf16(float lo, float hi) { unsigned r; asm volatile("v_cvt_pk_bf16_f32 %0, %1, %2" : "=v"(r) : "v"(lo), "v"(hi)); return r; }
; __device__ __forceinline__ float bf_lo(unsigned u) { return __uint_as_float(u << 16); }
; __device__ __forceinline__ float bf_hi(unsigned u) { return __uint_as_float(u & 0xffff0000u); }
;     __device__ __forceinline__ void operator()(const f32x4 (&acc)[2][2][4][2], const Unit& u, int wr, int wc, int fr, int fq) const {
;     ...
;             const unsigned mo = (off >> 11) * 1024u + (off & 2047u);
; #pragma unroll
;             for (int m = 0; m < 4; ++m)
; #pragma unroll
;                 for (int bj = 0; bj < 2; ++bj) { const u32x4 s = sb[m][bj];
;                     const f32x4 a0 = acc[ai][bj][m][0], a1 = acc[ai][bj][m][1];
;                     u32x4 w; w.x = cvt_pk_bf16(a0[0] * bf_lo(s.x), a0[1] * bf_hi(s.x)); w.y = cvt_pk_bf16(a0[2] * bf_lo(s.y), a0[3] * bf_hi(s.y));
;                     w.z = cvt_pk_bf16(a1[0] * bf_lo(s.z), a1[1] * bf_hi(s.z)); w.w = cvt_pk_bf16(a1[2] * bf_lo(s.w), a1[3] * bf_hi(s.w));
;                     *(u32x4*)(merged + mo + m * 16 * 1024 + bj * HALF) = w; }
;             off += 128u * 2048u; }
	v_lshlrev_b32_e32 v90, 16, v136
	v_mul_f32_e32 v89, v91, v89
	v_cvt_pk_bf16_f32 v95, v88, v89
	v_add_co_u32_e32 v88, vcc, s72, v120
	v_mul_f32_e32 v84, v84, v90
	v_and_b32_e32 v90, 0xffff0000, v136
	v_addc_co_u32_e32 v89, vcc, 0, v121, vcc
	v_mul_f32_e32 v85, v85, v90
	global_store_dwordx4 v[88:89], v[92:95], off
	v_cvt_pk_bf16_f32 v84, v84, v85
	v_lshlrev_b32_e32 v85, 16, v137
	v_mul_f32_e32 v85, v86, v85
	v_and_b32_e32 v86, 0xffff0000, v137
	v_mul_f32_e32 v86, v87, v86
	v_cvt_pk_bf16_f32 v85, v85, v86
	v_lshlrev_b32_e32 v86, 16, v138
	v_mul_f32_e32 v76, v76, v86
	v_and_b32_e32 v86, 0xffff0000, v138
	v_mul_f32_e32 v77, v77, v86
	v_cvt_pk_bf16_f32 v86, v76, v77
	v_lshlrev_b32_e32 v76, 16, v139
	v_and_b32_e32 v77, 0xffff0000, v139
	v_mul_f32_e32 v76, v78, v76
	v_mul_f32_e32 v77, v79, v77
	v_cvt_pk_bf16_f32 v87, v76, v77
	v_lshlrev_b32_e32 v76, 16, v132
	v_and_b32_e32 v77, 0xffff0000, v132
	v_mul_f32_e32 v76, v80, v76
	v_mul_f32_e32 v77, v81, v77
	global_store_dwordx4 v[88:89], v[84:87], off offset:256
	v_cvt_pk_bf16_f32 v76, v76, v77
	v_lshlrev_b32_e32 v77, 16, v133
	v_and_b32_e32 v78, 0xffff0000, v133
	v_mul_f32_e32 v77, v82, v77
	v_mul_f32_e32 v78, v83, v78
	v_cvt_pk_bf16_f32 v77, v77, v78
	v_lshlrev_b32_e32 v78, 16, v134
	v_mul_f32_e32 v72, v72, v78
	v_and_b32_e32 v78, 0xffff0000, v134
	v_mul_f32_e32 v73, v73, v78
	v_cvt_pk_bf16_f32 v78, v72, v73
	v_lshlrev_b32_e32 v72, 16, v135
	v_mul_f32_e32 v72, v74, v72
	v_and_b32_e32 v73, 0xffff0000, v135
	v_lshlrev_b32_e32 v74, 16, v128
	v_mul_f32_e32 v73, v75, v73
	v_cvt_pk_bf16_f32 v79, v72, v73
	v_add_co_u32_e32 v72, vcc, s0, v120
	v_mul_f32_e32 v68, v68, v74
	v_and_b32_e32 v74, 0xffff0000, v128
	v_addc_co_u32_e32 v73, vcc, 0, v121, vcc
	v_mul_f32_e32 v69, v69, v74
	global_store_dwordx4 v[72:73], v[76:79], off
	v_cvt_pk_bf16_f32 v68, v68, v69
	v_lshlrev_b32_e32 v69, 16, v129
	v_mul_f32_e32 v69, v70, v69
	v_and_b32_e32 v70, 0xffff0000, v129
	v_mul_f32_e32 v70, v71, v70
	v_cvt_pk_bf16_f32 v69, v69, v70
	v_lshlrev_b32_e32 v70, 16, v130
	v_mul_f32_e32 v64, v64, v70
	v_and_b32_e32 v70, 0xffff0000, v130
	v_mul_f32_e32 v65, v65, v70
	v_cvt_pk_bf16_f32 v70, v64, v65
	v_lshlrev_b32_e32 v64, 16, v131
	v_and_b32_e32 v65, 0xffff0000, v131
	v_mul_f32_e32 v64, v66, v64
	v_mul_f32_e32 v65, v67, v65
	v_cvt_pk_bf16_f32 v71, v64, v65
	global_store_dwordx4 v[72:73], v[68:71], off offset:256
	v_add_u32_e32 v194, 0x40000, v218
	v_lshrrev_b32_e32 v96, 1, v194
	v_and_b32_e32 v96, 0x7ffffc00, v96
	v_and_b32_e32 v97, 0x7ff, v194
	v_add_u32_e32 v194, v96, v97
	s_waitcnt vmcnt(15)
	v_lshlrev_b32_e32 v96, 16, v160
	v_and_b32_e32 v160, 0xffff0000, v160
	v_mul_f32_e32 v60, v60, v96
	v_mul_f32_e32 v61, v61, v160
	v_cvt_pk_bf16_f32 v60, v60, v61
	v_lshlrev_b32_e32 v61, 16, v161
	v_mul_f32_e32 v61, v62, v61
	v_and_b32_e32 v62, 0xffff0000, v161
	v_mul_f32_e32 v62, v63, v62
	v_cvt_pk_bf16_f32 v61, v61, v62
	v_lshlrev_b32_e32 v62, 16, v162
	v_mul_f32_e32 v56, v56, v62
	v_and_b32_e32 v62, 0xffff0000, v162
	v_mul_f32_e32 v57, v57, v62
	v_cvt_pk_bf16_f32 v62, v56, v57
	v_lshlrev_b32_e32 v56, 16, v163
	v_mul_f32_e32 v56, v58, v56
	v_and_b32_e32 v57, 0xffff0000, v163
	s_waitcnt vmcnt(14)
	v_lshlrev_b32_e32 v58, 16, v164
	v_mul_f32_e32 v57, v59, v57
	v_mul_f32_e32 v52, v52, v58
	v_and_b32_e32 v58, 0xffff0000, v164
	v_cvt_pk_bf16_f32 v63, v56, v57
	v_lshl_add_u64 v[56:57], v[194:195], 1, s[12:13]
	v_mul_f32_e32 v53, v53, v58
	global_store_dwordx4 v[56:57], v[60:63], off
	v_cvt_pk_bf16_f32 v52, v52, v53
	v_lshlrev_b32_e32 v53, 16, v165
	v_mul_f32_e32 v53, v54, v53
	v_and_b32_e32 v54, 0xffff0000, v165
	v_mul_f32_e32 v54, v55, v54
	v_cvt_pk_bf16_f32 v53, v53, v54
	v_lshlrev_b32_e32 v54, 16, v166
	v_mul_f32_e32 v44, v44, v54
	v_and_b32_e32 v54, 0xffff0000, v166
	v_mul_f32_e32 v45, v45, v54
	v_cvt_pk_bf16_f32 v54, v44, v45
	v_lshlrev_b32_e32 v44, 16, v167
	v_and_b32_e32 v45, 0xffff0000, v167
	v_mul_f32_e32 v44, v46, v44
	v_mul_f32_e32 v45, v47, v45
	v_cvt_pk_bf16_f32 v55, v44, v45
	s_waitcnt vmcnt(14)
	v_lshlrev_b32_e32 v44, 16, v168
	v_and_b32_e32 v45, 0xffff0000, v168
	v_mul_f32_e32 v44, v48, v44
	v_mul_f32_e32 v45, v49, v45
	global_store_dwordx4 v[56:57], v[52:55], off offset:256
	v_cvt_pk_bf16_f32 v44, v44, v45
	v_lshlrev_b32_e32 v45, 16, v169
	v_and_b32_e32 v46, 0xffff0000, v169
	v_mul_f32_e32 v45, v50, v45
	v_mul_f32_e32 v46, v51, v46
	v_cvt_pk_bf16_f32 v45, v45, v46
	v_lshlrev_b32_e32 v46, 16, v170
	v_mul_f32_e32 v40, v40, v46
	v_and_b32_e32 v46, 0xffff0000, v170
	v_mul_f32_e32 v41, v41, v46
	v_cvt_pk_bf16_f32 v46, v40, v41
	v_lshlrev_b32_e32 v40, 16, v171
	v_mul_f32_e32 v40, v42, v40
	v_and_b32_e32 v41, 0xffff0000, v171
	s_waitcnt vmcnt(14)
; __device__ __forceinline__ unsigned cvt_pk_bf16(float lo, float hi) { unsigned r; asm volatile("v_cvt_pk_bf16_f32 %0, %1, %2" : "=v"(r) : "v"(lo), "v"(hi)); return r; }
; __device__ __forceinline__ float bf_lo(unsigned u) { return __uint_as_float(u << 16); }
; __device__ __forceinline__ float bf_hi(unsigned u) { return __uint_as_float(u & 0xffff0000u); }
;     __device__ __forceinline__ void operator()(const f32x4 (&acc)[2][2][4][2], const Unit& u, int wr, int wc, int fr, int fq) const {
;     ...
;             for (int m = 0; m < 4; ++m)
; #pragma unroll
;                 for (int bj = 0; bj < 2; ++bj) { const u32x4 s = sb[m][bj];
;                     const f32x4 a0 = acc[ai][bj][m][0], a1 = acc[ai][bj][m][1];
;                     u32x4 w; w.x = cvt_pk_bf16(a0[0] * bf_lo(s.x), a0[1] * bf_hi(s.x)); w.y = cvt_pk_bf16(a0[2] * bf_lo(s.y), a0[3] * bf_hi(s.y));
;                     w.z = cvt_pk_bf16(a1[0] * bf_lo(s.z), a1[1] * bf_hi(s.z)); w.w = cvt_pk_bf16(a1[2] * bf_lo(s.w), a1[3] * bf_hi(s.w));
;                     *(u32x4*)(merged + mo + m * 16 * 1024 + bj * HALF) = w; }
;             off += 128u * 2048u; }
	v_lshlrev_b32_e32 v42, 16, v172
	v_mul_f32_e32 v41, v43, v41
	v_cvt_pk_bf16_f32 v47, v40, v41
	v_add_co_u32_e32 v40, vcc, s1, v56
	v_mul_f32_e32 v36, v36, v42
	v_and_b32_e32 v42, 0xffff0000, v172
	v_addc_co_u32_e32 v41, vcc, 0, v57, vcc
	v_mul_f32_e32 v37, v37, v42
	global_store_dwordx4 v[40:41], v[44:47], off
	v_cvt_pk_bf16_f32 v36, v36, v37
	v_lshlrev_b32_e32 v37, 16, v173
	v_mul_f32_e32 v37, v38, v37
	v_and_b32_e32 v38, 0xffff0000, v173
	v_mul_f32_e32 v38, v39, v38
	v_cvt_pk_bf16_f32 v37, v37, v38
	v_lshlrev_b32_e32 v38, 16, v174
	v_mul_f32_e32 v28, v28, v38
	v_and_b32_e32 v38, 0xffff0000, v174
	v_mul_f32_e32 v29, v29, v38
	v_cvt_pk_bf16_f32 v38, v28, v29
	v_lshlrev_b32_e32 v28, 16, v175
	v_and_b32_e32 v29, 0xffff0000, v175
	v_mul_f32_e32 v28, v30, v28
	v_mul_f32_e32 v29, v31, v29
	v_cvt_pk_bf16_f32 v39, v28, v29
	s_waitcnt vmcnt(14)
	v_lshlrev_b32_e32 v28, 16, v176
	v_and_b32_e32 v29, 0xffff0000, v176
	v_mul_f32_e32 v28, v32, v28
	v_mul_f32_e32 v29, v33, v29
	global_store_dwordx4 v[40:41], v[36:39], off offset:256
	v_cvt_pk_bf16_f32 v28, v28, v29
	v_lshlrev_b32_e32 v29, 16, v177
	v_and_b32_e32 v30, 0xffff0000, v177
	v_mul_f32_e32 v29, v34, v29
	v_mul_f32_e32 v30, v35, v30
	v_cvt_pk_bf16_f32 v29, v29, v30
	v_lshlrev_b32_e32 v30, 16, v178
	v_mul_f32_e32 v24, v24, v30
	v_and_b32_e32 v30, 0xffff0000, v178
	v_mul_f32_e32 v25, v25, v30
	v_cvt_pk_bf16_f32 v30, v24, v25
	v_lshlrev_b32_e32 v24, 16, v179
	v_mul_f32_e32 v24, v26, v24
	v_and_b32_e32 v25, 0xffff0000, v179
	s_waitcnt vmcnt(14)
	v_lshlrev_b32_e32 v26, 16, v180
	v_mul_f32_e32 v25, v27, v25
	v_cvt_pk_bf16_f32 v31, v24, v25
	v_add_co_u32_e32 v24, vcc, s72, v56
	v_mul_f32_e32 v20, v20, v26
	v_and_b32_e32 v26, 0xffff0000, v180
	v_addc_co_u32_e32 v25, vcc, 0, v57, vcc
	v_mul_f32_e32 v21, v21, v26
	global_store_dwordx4 v[24:25], v[28:31], off
	v_cvt_pk_bf16_f32 v20, v20, v21
	v_lshlrev_b32_e32 v21, 16, v181
	v_mul_f32_e32 v21, v22, v21
	v_and_b32_e32 v22, 0xffff0000, v181
	v_mul_f32_e32 v22, v23, v22
	v_cvt_pk_bf16_f32 v21, v21, v22
	v_lshlrev_b32_e32 v22, 16, v182
	v_mul_f32_e32 v12, v12, v22
	v_and_b32_e32 v22, 0xffff0000, v182
	v_mul_f32_e32 v13, v13, v22
	v_cvt_pk_bf16_f32 v22, v12, v13
	v_lshlrev_b32_e32 v12, 16, v183
	v_and_b32_e32 v13, 0xffff0000, v183
	v_mul_f32_e32 v12, v14, v12
	v_mul_f32_e32 v13, v15, v13
	v_cvt_pk_bf16_f32 v23, v12, v13
	s_waitcnt vmcnt(14)
	v_lshlrev_b32_e32 v12, 16, v184
	v_and_b32_e32 v13, 0xffff0000, v184
	v_mul_f32_e32 v12, v16, v12
	v_mul_f32_e32 v13, v17, v13
	global_store_dwordx4 v[24:25], v[20:23], off offset:256
	v_cvt_pk_bf16_f32 v12, v12, v13
	v_lshlrev_b32_e32 v13, 16, v185
	v_and_b32_e32 v14, 0xffff0000, v185
	v_mul_f32_e32 v13, v18, v13
	v_mul_f32_e32 v14, v19, v14
	v_cvt_pk_bf16_f32 v13, v13, v14
	v_lshlrev_b32_e32 v14, 16, v186
	v_mul_f32_e32 v8, v8, v14
	v_and_b32_e32 v14, 0xffff0000, v186
	v_mul_f32_e32 v9, v9, v14
	v_cvt_pk_bf16_f32 v14, v8, v9
	v_lshlrev_b32_e32 v8, 16, v187
	v_mul_f32_e32 v8, v10, v8
	v_and_b32_e32 v9, 0xffff0000, v187
	s_waitcnt vmcnt(14)
	v_lshlrev_b32_e32 v10, 16, v188
	v_mul_f32_e32 v9, v11, v9
	v_cvt_pk_bf16_f32 v15, v8, v9
	v_add_co_u32_e32 v8, vcc, s0, v56
	v_mul_f32_e32 v4, v4, v10
	v_and_b32_e32 v10, 0xffff0000, v188
	v_addc_co_u32_e32 v9, vcc, 0, v57, vcc
	v_mul_f32_e32 v5, v5, v10
	global_store_dwordx4 v[8:9], v[12:15], off
	v_cvt_pk_bf16_f32 v4, v4, v5
	v_lshlrev_b32_e32 v5, 16, v189
	v_mul_f32_e32 v5, v6, v5
	v_and_b32_e32 v6, 0xffff0000, v189
	v_mul_f32_e32 v6, v7, v6
	v_cvt_pk_bf16_f32 v5, v5, v6
	v_lshlrev_b32_e32 v6, 16, v190
	v_mul_f32_e32 v0, v0, v6
	v_and_b32_e32 v6, 0xffff0000, v190
	v_mul_f32_e32 v1, v1, v6
	v_cvt_pk_bf16_f32 v6, v0, v1
	v_lshlrev_b32_e32 v0, 16, v191
	v_and_b32_e32 v1, 0xffff0000, v191
	s_mov_b64 s[0:1], -1
	s_andn2_b64 vcc, exec, s[6:7]
	v_mul_f32_e32 v0, v2, v0
	v_mul_f32_e32 v1, v3, v1
	v_cvt_pk_bf16_f32 v7, v0, v1
	global_store_dwordx4 v[8:9], v[4:7], off offset:256
	s_cbranch_vccnz .LBB0_414
	s_andn2_b64 vcc, exec, s[8:9]
	s_cbranch_vccnz .LBB0_413
	s_barrier
	s_branch .LBB0_413

; __device__ __forceinline__ unsigned cvt_pk_bf16(float lo, float hi) { unsigned r; asm volatile("v_cvt_pk_bf16_f32 %0, %1, %2" : "=v"(r) : "v"(lo), "v"(hi)); return r; }
;     __device__ __forceinline__ void operator()(const f32x4 (&acc)[2][2][4][2], const Unit& u, int wr, int wc, int fr, int fq) const {
;     ...
;             for (int m = 0; m < 4; ++m) { const size_t r = (size_t)(row0 + ai * HALF + m * 16); const float gt = gate[r];
; #pragma unroll
;                 for (int bj = 0; bj < 2; ++bj) { const f32x4 v0 = acc[ai][bj][m][0] * gt, v1 = acc[ai][bj][m][1] * gt;
;                     u32x4 w; w.x = cvt_pk_bf16(v0[0], v0[1]); w.y = cvt_pk_bf16(v0[2], v0[3]); w.z = cvt_pk_bf16(v1[0], v1[1]); w.w = cvt_pk_bf16(v1[2], v1[3]);
;                     *(u32x4*)(ye + r * 1024 + col0 + bj * HALF) = w; } }
.LBB0_851:
	v_lshl_add_u32 v136, s41, 8, v138
	v_ashrrev_i32_e32 v137, 31, v136
	v_lshl_add_u64 v[134:135], v[136:137], 2, s[12:13]
	global_load_dword v150, v[134:135], off
	global_load_dword v151, v[134:135], off offset:64
	global_load_dword v152, v[134:135], off offset:128
	global_load_dword v153, v[134:135], off offset:192
	global_load_dword v154, v[134:135], off offset:512
	global_load_dword v155, v[134:135], off offset:576
	global_load_dword v156, v[134:135], off offset:640
	global_load_dword v157, v[134:135], off offset:704
	s_lshl_b32 s0, s40, 8
	s_and_b32 s0, s0, 0x300
	v_or_b32_e32 v143, s0, v140
	v_lshlrev_b64 v[144:145], 11, v[136:137]
	v_lshlrev_b32_e32 v194, 1, v143
	s_mov_b32 s0, 0x40000
	s_waitcnt vmcnt(0)
	v_mov_b32_e32 v142, v150
	v_pk_mul_f32 v[124:125], v[124:125], v[142:143] op_sel_hi:[1,0]
	v_pk_mul_f32 v[120:121], v[120:121], v[142:143] op_sel_hi:[1,0]
	v_pk_mul_f32 v[126:127], v[126:127], v[142:143] op_sel_hi:[1,0]
	v_pk_mul_f32 v[146:147], v[122:123], v[142:143] op_sel_hi:[1,0]
	v_cvt_pk_bf16_f32 v122, v124, v125
	v_cvt_pk_bf16_f32 v123, v126, v127
	v_cvt_pk_bf16_f32 v124, v120, v121
	v_lshl_add_u64 v[120:121], s[10:11], 0, v[144:145]
	v_lshl_add_u64 v[120:121], v[120:121], 0, v[194:195]
	v_cvt_pk_bf16_f32 v125, v146, v147
	global_store_dwordx4 v[120:121], v[122:125], off
	v_pk_mul_f32 v[116:117], v[116:117], v[142:143] op_sel_hi:[1,0]
	v_pk_mul_f32 v[118:119], v[118:119], v[142:143] op_sel_hi:[1,0]
	v_pk_mul_f32 v[122:123], v[114:115], v[142:143] op_sel_hi:[1,0]
	v_pk_mul_f32 v[114:115], v[112:113], v[142:143] op_sel_hi:[1,0]
	v_cvt_pk_bf16_f32 v112, v116, v117
	v_cvt_pk_bf16_f32 v113, v118, v119
	s_nop 0
	v_cvt_pk_bf16_f32 v114, v114, v115
	v_cvt_pk_bf16_f32 v115, v122, v123
	global_store_dwordx4 v[120:121], v[112:115], off offset:256
	s_nop 1
	v_or_b32_e32 v112, 16, v136
	v_ashrrev_i32_e32 v113, 31, v112
	v_lshl_add_u64 v[114:115], v[112:113], 2, s[12:13]
	v_mov_b32_e32 v114, v151
	v_lshlrev_b64 v[112:113], 11, v[112:113]
	v_pk_mul_f32 v[108:109], v[108:109], v[114:115] op_sel_hi:[1,0]
	v_pk_mul_f32 v[116:117], v[106:107], v[114:115] op_sel_hi:[1,0]
	v_pk_mul_f32 v[106:107], v[104:105], v[114:115] op_sel_hi:[1,0]
	v_cvt_pk_bf16_f32 v104, v108, v109
	v_lshl_add_u64 v[108:109], s[10:11], 0, v[112:113]
	v_pk_mul_f32 v[110:111], v[110:111], v[114:115] op_sel_hi:[1,0]
	v_lshl_add_u64 v[108:109], v[108:109], 0, v[194:195]
	v_cvt_pk_bf16_f32 v105, v110, v111
	v_cvt_pk_bf16_f32 v106, v106, v107
	v_cvt_pk_bf16_f32 v107, v116, v117
	global_store_dwordx4 v[108:109], v[104:107], off
	v_pk_mul_f32 v[100:101], v[100:101], v[114:115] op_sel_hi:[1,0]
	v_pk_mul_f32 v[102:103], v[102:103], v[114:115] op_sel_hi:[1,0]
	v_pk_mul_f32 v[104:105], v[98:99], v[114:115] op_sel_hi:[1,0]
	v_pk_mul_f32 v[98:99], v[96:97], v[114:115] op_sel_hi:[1,0]
	v_cvt_pk_bf16_f32 v96, v100, v101
	v_cvt_pk_bf16_f32 v97, v102, v103
	s_nop 0
	v_cvt_pk_bf16_f32 v98, v98, v99
	v_cvt_pk_bf16_f32 v99, v104, v105
	global_store_dwordx4 v[108:109], v[96:99], off offset:256
	s_nop 1
	v_or_b32_e32 v96, 32, v136
	v_ashrrev_i32_e32 v97, 31, v96
	v_lshl_add_u64 v[98:99], v[96:97], 2, s[12:13]
	v_mov_b32_e32 v98, v152
	v_lshlrev_b64 v[96:97], 11, v[96:97]
	v_pk_mul_f32 v[92:93], v[92:93], v[98:99] op_sel_hi:[1,0]
	v_pk_mul_f32 v[100:101], v[90:91], v[98:99] op_sel_hi:[1,0]
	v_pk_mul_f32 v[90:91], v[88:89], v[98:99] op_sel_hi:[1,0]
	v_cvt_pk_bf16_f32 v88, v92, v93
	v_lshl_add_u64 v[92:93], s[10:11], 0, v[96:97]
	v_pk_mul_f32 v[94:95], v[94:95], v[98:99] op_sel_hi:[1,0]
	v_lshl_add_u64 v[92:93], v[92:93], 0, v[194:195]
	v_cvt_pk_bf16_f32 v89, v94, v95
	v_cvt_pk_bf16_f32 v90, v90, v91
	v_cvt_pk_bf16_f32 v91, v100, v101
	global_store_dwordx4 v[92:93], v[88:91], off
	v_pk_mul_f32 v[84:85], v[84:85], v[98:99] op_sel_hi:[1,0]
	v_pk_mul_f32 v[86:87], v[86:87], v[98:99] op_sel_hi:[1,0]
	v_pk_mul_f32 v[88:89], v[82:83], v[98:99] op_sel_hi:[1,0]
	v_pk_mul_f32 v[82:83], v[80:81], v[98:99] op_sel_hi:[1,0]
	v_cvt_pk_bf16_f32 v80, v84, v85
	v_cvt_pk_bf16_f32 v81, v86, v87
	s_nop 0
	v_cvt_pk_bf16_f32 v82, v82, v83
	v_cvt_pk_bf16_f32 v83, v88, v89
	global_store_dwordx4 v[92:93], v[80:83], off offset:256
	s_nop 1
	v_or_b32_e32 v80, 48, v136
	v_ashrrev_i32_e32 v81, 31, v80
	v_lshl_add_u64 v[82:83], v[80:81], 2, s[12:13]
	v_mov_b32_e32 v82, v153
	v_lshlrev_b64 v[80:81], 11, v[80:81]
	v_pk_mul_f32 v[76:77], v[76:77], v[82:83] op_sel_hi:[1,0]
	v_pk_mul_f32 v[84:85], v[74:75], v[82:83] op_sel_hi:[1,0]
	v_pk_mul_f32 v[74:75], v[72:73], v[82:83] op_sel_hi:[1,0]
	v_cvt_pk_bf16_f32 v72, v76, v77
	v_lshl_add_u64 v[76:77], s[10:11], 0, v[80:81]
	v_pk_mul_f32 v[78:79], v[78:79], v[82:83] op_sel_hi:[1,0]
	v_lshl_add_u64 v[76:77], v[76:77], 0, v[194:195]
	v_cvt_pk_bf16_f32 v73, v78, v79
	v_cvt_pk_bf16_f32 v74, v74, v75
	v_cvt_pk_bf16_f32 v75, v84, v85
	global_store_dwordx4 v[76:77], v[72:75], off
; __device__ __forceinline__ unsigned cvt_pk_bf16(float lo, float hi) { unsigned r; asm volatile("v_cvt_pk_bf16_f32 %0, %1, %2" : "=v"(r) : "v"(lo), "v"(hi)); return r; }
;     __device__ __forceinline__ void operator()(const f32x4 (&acc)[2][2][4][2], const Unit& u, int wr, int wc, int fr, int fq) const {
;     ...
;             for (int m = 0; m < 4; ++m) { const size_t r = (size_t)(row0 + ai * HALF + m * 16); const float gt = gate[r];
; #pragma unroll
;                 for (int bj = 0; bj < 2; ++bj) { const f32x4 v0 = acc[ai][bj][m][0] * gt, v1 = acc[ai][bj][m][1] * gt;
;                     u32x4 w; w.x = cvt_pk_bf16(v0[0], v0[1]); w.y = cvt_pk_bf16(v0[2], v0[3]); w.z = cvt_pk_bf16(v1[0], v1[1]); w.w = cvt_pk_bf16(v1[2], v1[3]);
;                     *(u32x4*)(ye + r * 1024 + col0 + bj * HALF) = w; } }
	v_pk_mul_f32 v[70:71], v[70:71], v[82:83] op_sel_hi:[1,0]
	v_pk_mul_f32 v[68:69], v[68:69], v[82:83] op_sel_hi:[1,0]
	v_pk_mul_f32 v[72:73], v[66:67], v[82:83] op_sel_hi:[1,0]
	v_pk_mul_f32 v[66:67], v[64:65], v[82:83] op_sel_hi:[1,0]
	v_cvt_pk_bf16_f32 v64, v68, v69
	v_cvt_pk_bf16_f32 v65, v70, v71
	s_nop 0
	v_cvt_pk_bf16_f32 v66, v66, v67
	v_cvt_pk_bf16_f32 v67, v72, v73
	global_store_dwordx4 v[76:77], v[64:67], off offset:256
	s_nop 1
	v_mov_b32_e32 v64, v154
	v_pk_mul_f32 v[62:63], v[62:63], v[64:65] op_sel_hi:[1,0]
	v_pk_mul_f32 v[60:61], v[60:61], v[64:65] op_sel_hi:[1,0]
	v_pk_mul_f32 v[66:67], v[58:59], v[64:65] op_sel_hi:[1,0]
	v_pk_mul_f32 v[58:59], v[56:57], v[64:65] op_sel_hi:[1,0]
	v_cvt_pk_bf16_f32 v56, v60, v61
	v_cvt_pk_bf16_f32 v57, v62, v63
	v_add_co_u32_e32 v62, vcc, s0, v120
	v_cvt_pk_bf16_f32 v58, v58, v59
	v_cvt_pk_bf16_f32 v59, v66, v67
	v_lshl_add_u64 v[60:61], v[120:121], 0, s[92:93]
	s_nop 0
	v_addc_co_u32_e32 v63, vcc, 0, v121, vcc
	global_store_dwordx4 v[62:63], v[56:59], off
	v_pk_mul_f32 v[54:55], v[54:55], v[64:65] op_sel_hi:[1,0]
	v_pk_mul_f32 v[52:53], v[52:53], v[64:65] op_sel_hi:[1,0]
	v_pk_mul_f32 v[56:57], v[50:51], v[64:65] op_sel_hi:[1,0]
	v_pk_mul_f32 v[50:51], v[48:49], v[64:65] op_sel_hi:[1,0]
	v_cvt_pk_bf16_f32 v48, v52, v53
	v_cvt_pk_bf16_f32 v49, v54, v55
	s_mov_b64 s[0:1], 0x48000
	v_cvt_pk_bf16_f32 v50, v50, v51
	v_cvt_pk_bf16_f32 v51, v56, v57
	global_store_dwordx4 v[60:61], v[48:51], off offset:256
	s_nop 1
	v_mov_b32_e32 v48, v155
	v_pk_mul_f32 v[44:45], v[44:45], v[48:49] op_sel_hi:[1,0]
	v_pk_mul_f32 v[46:47], v[46:47], v[48:49] op_sel_hi:[1,0]
	v_pk_mul_f32 v[50:51], v[42:43], v[48:49] op_sel_hi:[1,0]
	v_pk_mul_f32 v[42:43], v[40:41], v[48:49] op_sel_hi:[1,0]
	v_cvt_pk_bf16_f32 v40, v44, v45
	v_lshl_add_u64 v[44:45], v[120:121], 0, s[0:1]
	s_mov_b32 s0, 0x48000
	v_cvt_pk_bf16_f32 v41, v46, v47
	v_add_co_u32_e32 v46, vcc, s0, v120
	v_cvt_pk_bf16_f32 v42, v42, v43
	v_cvt_pk_bf16_f32 v43, v50, v51
	v_pk_mul_f32 v[38:39], v[38:39], v[48:49] op_sel_hi:[1,0]
	s_nop 0
	v_addc_co_u32_e32 v47, vcc, 0, v121, vcc
	global_store_dwordx4 v[46:47], v[40:43], off
	v_pk_mul_f32 v[36:37], v[36:37], v[48:49] op_sel_hi:[1,0]
	s_mov_b64 s[0:1], 0x50000
	v_pk_mul_f32 v[40:41], v[34:35], v[48:49] op_sel_hi:[1,0]
	v_pk_mul_f32 v[34:35], v[32:33], v[48:49] op_sel_hi:[1,0]
	v_cvt_pk_bf16_f32 v32, v36, v37
	v_cvt_pk_bf16_f32 v33, v38, v39
	s_nop 0
	v_cvt_pk_bf16_f32 v34, v34, v35
	v_cvt_pk_bf16_f32 v35, v40, v41
	global_store_dwordx4 v[44:45], v[32:35], off offset:256
	s_nop 1
	v_mov_b32_e32 v32, v156
	v_pk_mul_f32 v[28:29], v[28:29], v[32:33] op_sel_hi:[1,0]
	v_pk_mul_f32 v[30:31], v[30:31], v[32:33] op_sel_hi:[1,0]
	v_pk_mul_f32 v[34:35], v[26:27], v[32:33] op_sel_hi:[1,0]
	v_pk_mul_f32 v[26:27], v[24:25], v[32:33] op_sel_hi:[1,0]
	v_cvt_pk_bf16_f32 v24, v28, v29
	v_lshl_add_u64 v[28:29], v[120:121], 0, s[0:1]
	s_mov_b32 s0, 0x50000
	v_cvt_pk_bf16_f32 v25, v30, v31
	v_add_co_u32_e32 v30, vcc, s0, v120
	v_cvt_pk_bf16_f32 v26, v26, v27
	v_cvt_pk_bf16_f32 v27, v34, v35
	v_pk_mul_f32 v[22:23], v[22:23], v[32:33] op_sel_hi:[1,0]
	s_nop 0
	v_addc_co_u32_e32 v31, vcc, 0, v121, vcc
	global_store_dwordx4 v[30:31], v[24:27], off
	v_pk_mul_f32 v[20:21], v[20:21], v[32:33] op_sel_hi:[1,0]
	s_mov_b64 s[0:1], 0x58000
	v_pk_mul_f32 v[24:25], v[18:19], v[32:33] op_sel_hi:[1,0]
	v_pk_mul_f32 v[18:19], v[16:17], v[32:33] op_sel_hi:[1,0]
	v_cvt_pk_bf16_f32 v16, v20, v21
	v_cvt_pk_bf16_f32 v17, v22, v23
	s_nop 0
	v_cvt_pk_bf16_f32 v18, v18, v19
	v_cvt_pk_bf16_f32 v19, v24, v25
	global_store_dwordx4 v[28:29], v[16:19], off offset:256
	s_nop 1
	v_mov_b32_e32 v16, v157
	v_pk_mul_f32 v[12:13], v[12:13], v[16:17] op_sel_hi:[1,0]
	v_pk_mul_f32 v[14:15], v[14:15], v[16:17] op_sel_hi:[1,0]
	v_pk_mul_f32 v[18:19], v[10:11], v[16:17] op_sel_hi:[1,0]
	v_pk_mul_f32 v[10:11], v[8:9], v[16:17] op_sel_hi:[1,0]
	v_cvt_pk_bf16_f32 v8, v12, v13
	v_lshl_add_u64 v[12:13], v[120:121], 0, s[0:1]
	s_mov_b32 s0, 0x58000
	v_cvt_pk_bf16_f32 v9, v14, v15
	v_add_co_u32_e32 v14, vcc, s0, v120
	v_cvt_pk_bf16_f32 v10, v10, v11
	v_cvt_pk_bf16_f32 v11, v18, v19
	s_mov_b64 s[0:1], -1
	s_nop 0
	v_addc_co_u32_e32 v15, vcc, 0, v121, vcc
	global_store_dwordx4 v[14:15], v[8:11], off
	s_andn2_b64 vcc, exec, s[6:7]
	v_pk_mul_f32 v[6:7], v[6:7], v[16:17] op_sel_hi:[1,0]
	v_pk_mul_f32 v[8:9], v[2:3], v[16:17] op_sel_hi:[1,0]
	v_pk_mul_f32 v[2:3], v[0:1], v[16:17] op_sel_hi:[1,0]
	v_pk_mul_f32 v[4:5], v[4:5], v[16:17] op_sel_hi:[1,0]
	s_nop 0
	v_cvt_pk_bf16_f32 v0, v4, v5
	v_cvt_pk_bf16_f32 v1, v6, v7
	v_cvt_pk_bf16_f32 v2, v2, v3
	v_cvt_pk_bf16_f32 v3, v8, v9
	global_store_dwordx4 v[12:13], v[0:3], off offset:256
	s_cbranch_vccnz .LBB0_844
	s_andn2_b64 vcc, exec, s[8:9]
	s_cbranch_vccnz .LBB0_843
	s_barrier
	s_branch .LBB0_843

; __device__ __forceinline__ unsigned xb_add(unsigned* p, unsigned v) { return __hip_atomic_fetch_add(p, v, __ATOMIC_RELAXED, __HIP_MEMORY_SCOPE_AGENT); }
; __device__ __forceinline__ void xcd_barrier(unsigned* bar, volatile LAS unsigned* st) {
;     ...
;             xb_add(&bar[XB_XGEN(x)], 1u);
;             asm volatile("s_waitcnt vmcnt(0)" ::: "memory");
.LBB0_1085:
	s_bcnt1_i32_b64 s4, s[4:5]
	v_mov_b32_e32 v0, s4
	global_atomic_add v223, v0, s[6:7] offset:1024
	s_getpc_b64 s[98:99]
